# merge: 11 gate loads between the two GEMMs issued together with counted waits instead of one vmcnt(0) round trip each
# baseline (speedup 1.0000x reference)
; DI int tid_() { int t = threadIdx.x; asm volatile("" : "+v"(t)); return t; }
; #define LASP __attribute__((address_space(3)))
; DI void gemm_dma(f32x4 (&acc)[4][4], const bf16_t* Ap, int lda, const bf16_t* Bp, int ldb, int K, char* lds) {
;   const int tid = tid_(), wave = __builtin_amdgcn_readfirstlane(tid >> 6), lane = tid & 63;
;   const int wm = wave >> 1, wn = wave & 1, l15 = lane & 15, quad = lane >> 4;
;   const int nk = K / 64;
;   const int lrow = lane >> 3, lpc = lane & 7;
;   const bf16_t* ga[4]; const bf16_t* gb[4];
; #pragma unroll
;   for (int i = 0; i < 4; ++i) {
;     const int row = (wave * 4 + i) * 8 + lrow; const int q = lpc ^ (row & 7);
;     ga[i] = Ap + (size_t)row * lda + q * 8; gb[i] = Bp + (size_t)row * ldb + q * 8;
;   }
;   auto issue = [&](int kt) {
;     char* sb = lds + (kt & 1) * 32768 + wave * 4096;
; #pragma unroll
;     for (int i = 0; i < 4; ++i) {
;       __builtin_amdgcn_global_load_lds((const unsigned*)(ga[i] + kt * 64), (LASP unsigned*)(sb + i * 1024), 16, 0, 0);
;       __builtin_amdgcn_global_load_lds((const unsigned*)(gb[i] + kt * 64), (LASP unsigned*)(sb + 16384 + i * 1024), 16, 0, 0);
;     }
;   };
;   const int sw = l15 & 7;
;   const unsigned lbase = (unsigned)(size_t)(LASP char*)lds;
;   const unsigned a0 = (unsigned)((wm * 64 + l15) * 128 + ((quad ^ sw) * 16)), a1 = (unsigned)((wm * 64 + l15) * 128 + (((4 + quad) ^ sw) * 16));
;   const unsigned b0 = 16384u + (unsigned)((wn * 64 + l15) * 128 + ((quad ^ sw) * 16)), b1 = 16384u + (unsigned)((wn * 64 + l15) * 128 + (((4 + quad) ^ sw) * 16));
;   asm volatile("s_waitcnt vmcnt(0)" ::: "memory");
;   __builtin_amdgcn_s_barrier();
;   asm volatile("" ::: "memory");
;   issue(0);
; DI void phase_merge(const Params& p, int l, char* lds) {
;     ...
;   for (int r = 0;; ++r) {
;     const int g = xcd_tile(r, 128 * 8); if (g < 0) break;
;     int mt, nt; tile_decode(g, 128, 8, mt, nt);
;     f32x4 a1[4][4]; zero_acc(a1);
;     gemm_dma(a1, p.o_r + (size_t)mt * 128 * 512, 512, p.wt_brr + (size_t)nt * 128 * 512, 512, 512, lds);
.LBB0_722:
	s_and_b32 s1, s0, 63
	s_lshr_b32 s0, s0, 3
	s_and_b32 s0, s0, 0xffffff8
	s_sub_i32 s2, 0x80, s0
	s_min_i32 s2, s2, 8
	s_abs_i32 s20, s2
	v_cvt_f32_u32_e32 v0, s20
	s_sub_i32 s21, 0, s20
	s_ashr_i32 s3, s2, 31
	v_mov_b32_e32 v10, v212
	v_rcp_iflag_f32_e32 v0, v0
	s_waitcnt vmcnt(0)
	s_barrier
	v_mul_f32_e32 v0, 0x4f7ffffe, v0
	v_cvt_u32_f32_e32 v0, v0
	v_bfe_u32 v11, v10, 4, 2
	v_and_b32_e32 v12, 7, v10
	v_readfirstlane_b32 s22, v0
	s_mul_i32 s21, s21, s22
	s_mul_hi_u32 s21, s22, s21
	s_add_i32 s22, s22, s21
	s_mul_hi_u32 s21, s1, s22
	s_mul_i32 s22, s21, s20
	s_sub_i32 s22, s1, s22
	s_add_i32 s23, s21, 1
	s_sub_i32 s24, s22, s20
	s_cmp_ge_u32 s22, s20
	s_cselect_b32 s21, s23, s21
	s_cselect_b32 s22, s24, s22
	s_add_i32 s23, s21, 1
	s_cmp_ge_u32 s22, s20
	s_cselect_b32 s20, s23, s21
	s_xor_b32 s20, s20, s3
	s_sub_i32 s22, s20, s3
	s_mul_i32 s2, s22, s2
	s_add_i32 s0, s0, s1
	s_sub_i32 s24, s0, s2
	s_ashr_i32 s25, s24, 31
	s_lshl_b64 s[0:1], s[24:25], 17
	s_add_u32 s26, s52, s0
	s_addc_u32 s27, s53, s1
	s_ashr_i32 s23, s22, 31
	s_lshl_b64 s[2:3], s[22:23], 17
	s_add_u32 s30, s74, s2
	v_readfirstlane_b32 s21, v10
	s_addc_u32 s31, s75, s3
	s_ashr_i32 s20, s21, 6
	v_bfe_u32 v0, v10, 3, 3
	v_lshl_or_b32 v2, s20, 5, v0
	v_bitop3_b32 v0, v0, v10, 7 bitop3:0x78
	v_lshlrev_b32_e32 v0, 4, v0
	v_ashrrev_i32_e32 v3, 31, v2
	v_lshl_add_u64 v[4:5], s[26:27], 0, v[0:1]
	v_lshl_add_u64 v[6:7], s[30:31], 0, v[0:1]
	v_lshlrev_b64 v[8:9], 10, v[2:3]
	v_lshl_add_u64 v[80:81], v[4:5], 0, v[8:9]
	v_lshl_add_u64 v[78:79], v[6:7], 0, v[8:9]
	v_or_b32_e32 v8, 8, v2
	v_ashrrev_i32_e32 v9, 31, v8
	s_lshl_b32 s40, s20, 12
	v_lshlrev_b64 v[8:9], 10, v[8:9]
	s_add_i32 s41, s40, 0x4000
	s_mov_b32 m0, s40
	v_lshl_add_u64 v[76:77], v[4:5], 0, v[8:9]
	v_lshl_add_u64 v[74:75], v[6:7], 0, v[8:9]
	v_or_b32_e32 v8, 16, v2
	global_load_lds_dwordx4 v[80:81], off
	s_mov_b32 m0, s41
	s_or_b32 s44, s40, 0x400
	v_ashrrev_i32_e32 v9, 31, v8
	global_load_lds_dwordx4 v[78:79], off
	s_mov_b32 m0, s44
	s_add_i32 s45, s40, 0x4400
	v_lshlrev_b64 v[8:9], 10, v[8:9]
	v_or_b32_e32 v2, 24, v2
	global_load_lds_dwordx4 v[76:77], off
	s_mov_b32 m0, s45
	s_or_b32 s46, s40, 0x800
	v_lshl_add_u64 v[72:73], v[4:5], 0, v[8:9]
	v_ashrrev_i32_e32 v3, 31, v2
	global_load_lds_dwordx4 v[74:75], off
	s_mov_b32 m0, s46
	s_add_i32 s42, s40, 0x4800
	v_lshl_add_u64 v[70:71], v[6:7], 0, v[8:9]
	v_lshlrev_b64 v[2:3], 10, v[2:3]
	s_lshr_b32 s23, s21, 1
	global_load_lds_dwordx4 v[72:73], off
	s_mov_b32 m0, s42
	s_or_b32 s43, s40, 0xc00
	v_lshl_add_u64 v[68:69], v[4:5], 0, v[2:3]
	v_lshl_add_u64 v[66:67], v[6:7], 0, v[2:3]
	v_and_b32_e32 v2, 15, v10
	s_and_b32 s23, s23, 0x1ffffc0
	global_load_lds_dwordx4 v[70:71], off
	s_mov_b32 m0, s43
	s_add_i32 s31, s40, 0x4c00
	v_or_b32_e32 v0, s23, v2
	v_bitop3_b32 v3, v11, v10, 7 bitop3:0x78
	v_bitop3_b32 v4, v11, v12, 4 bitop3:0x36
	v_and_or_b32 v2, s21, 64, v2
	global_load_lds_dwordx4 v[68:69], off
	s_mov_b32 m0, s31
	v_lshlrev_b32_e32 v0, 7, v0
	v_lshlrev_b32_e32 v3, 4, v3
	v_lshlrev_b32_e32 v4, 4, v4
	v_lshlrev_b32_e32 v2, 7, v2
	global_load_lds_dwordx4 v[66:67], off
	s_add_i32 s21, s40, 0x8000
	v_or_b32_e32 v82, v0, v3
	v_or_b32_e32 v86, v2, v3
	v_or_b32_e32 v87, v2, v4
	s_waitcnt vmcnt(0)
	s_barrier
	s_add_i32 s20, s40, 0xc000
	v_lshl_add_u64 v[2:3], v[80:81], 0, s[28:29]
	s_mov_b32 m0, s21
	s_add_i32 s23, s40, 0x8400
	global_load_lds_dwordx4 v[2:3], off
	v_lshl_add_u64 v[2:3], v[78:79], 0, s[28:29]
	s_mov_b32 m0, s20
	s_add_i32 s25, s40, 0xc400
	global_load_lds_dwordx4 v[2:3], off
	v_lshl_add_u64 v[2:3], v[76:77], 0, s[28:29]
	s_mov_b32 m0, s23
	s_add_i32 s26, s40, 0x8800
	global_load_lds_dwordx4 v[2:3], off
	v_lshl_add_u64 v[2:3], v[74:75], 0, s[28:29]
	s_mov_b32 m0, s25
	s_add_i32 s27, s40, 0xc800
	global_load_lds_dwordx4 v[2:3], off
	v_lshl_add_u64 v[2:3], v[72:73], 0, s[28:29]
	s_mov_b32 m0, s26
	s_add_i32 s30, s40, 0x8c00
	global_load_lds_dwordx4 v[2:3], off
	v_lshl_add_u64 v[2:3], v[70:71], 0, s[28:29]
	s_mov_b32 m0, s27
	s_add_i32 s47, s40, 0xcc00
	global_load_lds_dwordx4 v[2:3], off
	v_lshl_add_u64 v[2:3], v[68:69], 0, s[28:29]
	s_mov_b32 m0, s30
	v_or_b32_e32 v0, v0, v4
	global_load_lds_dwordx4 v[2:3], off
	v_lshl_add_u64 v[2:3], v[66:67], 0, s[28:29]
	s_mov_b32 m0, s47
	v_or_b32_e32 v84, 0x4000, v86
	global_load_lds_dwordx4 v[2:3], off
	ds_read_b128 v[2:5], v82
	ds_read_b128 v[6:9], v82 offset:2048
	ds_read_b128 v[10:13], v82 offset:4096
	ds_read_b128 v[14:17], v82 offset:6144
	ds_read_b128 v[18:21], v84
	ds_read_b128 v[22:25], v84 offset:2048
	ds_read_b128 v[26:29], v84 offset:4096
	ds_read_b128 v[30:33], v84 offset:6144
	v_or_b32_e32 v83, 0x4000, v87
	ds_read_b128 v[34:37], v0
	ds_read_b128 v[38:41], v0 offset:2048
	ds_read_b128 v[46:49], v0 offset:4096
	ds_read_b128 v[62:65], v0 offset:6144
	ds_read_b128 v[50:53], v83
	ds_read_b128 v[54:57], v83 offset:2048
	ds_read_b128 v[58:61], v83 offset:4096
	ds_read_b128 v[88:91], v83 offset:6144
	s_waitcnt lgkmcnt(8)
	s_mov_b32 m0, s40
	v_mfma_f32_16x16x32_bf16 v[42:45], v[18:21], v[2:5], 0
	s_waitcnt lgkmcnt(0)
	s_waitcnt vmcnt(0)
	s_barrier
; DI void gemm_dma(f32x4 (&acc)[4][4], const bf16_t* Ap, int lda, const bf16_t* Bp, int ldb, int K, char* lds) {
;     ...
;   for (int kt = 0; kt < nk; ++kt) {
;     asm volatile("s_waitcnt vmcnt(0)" ::: "memory");
;     __builtin_amdgcn_s_barrier();
;     asm volatile("" ::: "memory");
;     if (kt + 1 < nk) issue(kt + 1);
;     const unsigned sa = lbase + (unsigned)((kt & 1) * 32768);
;     bf16x8 af[4], bfr[4], ag[4], bg[4];
;     asm volatile("ds_read_b128 %0, %8\n\tds_read_b128 %1, %8 offset:2048\n\tds_read_b128 %2, %8 offset:4096\n\tds_read_b128 %3, %8 offset:6144\n\t"
;                  "ds_read_b128 %4, %9\n\tds_read_b128 %5, %9 offset:2048\n\tds_read_b128 %6, %9 offset:4096\n\tds_read_b128 %7, %9 offset:6144"
;                  : "=&v"(af[0]), "=&v"(af[1]), "=&v"(af[2]), "=&v"(af[3]), "=&v"(bfr[0]), "=&v"(bfr[1]), "=&v"(bfr[2]), "=&v"(bfr[3])
;                  : "v"(sa + a0), "v"(sa + b0) : "memory");
;     asm volatile("ds_read_b128 %0, %16\n\tds_read_b128 %1, %16 offset:2048\n\tds_read_b128 %2, %16 offset:4096\n\tds_read_b128 %3, %16 offset:6144\n\t"
;                  "ds_read_b128 %4, %17\n\tds_read_b128 %5, %17 offset:2048\n\tds_read_b128 %6, %17 offset:4096\n\tds_read_b128 %7, %17 offset:6144\n\t"
;                  "s_waitcnt lgkmcnt(8)"
;                  : "=&v"(ag[0]), "=&v"(ag[1]), "=&v"(ag[2]), "=&v"(ag[3]), "=&v"(bg[0]), "=&v"(bg[1]), "=&v"(bg[2]), "=&v"(bg[3]),
;                    "+v"(af[0]), "+v"(af[1]), "+v"(af[2]), "+v"(af[3]), "+v"(bfr[0]), "+v"(bfr[1]), "+v"(bfr[2]), "+v"(bfr[3])
;                  : "v"(sa + a1), "v"(sa + b1) : "memory");
; #pragma unroll
;     for (int mi = 0; mi < 4; ++mi)
; #pragma unroll
;       for (int ni = 0; ni < 4; ++ni) acc[mi][ni] = __builtin_amdgcn_mfma_f32_16x16x32_bf16(bfr[ni], af[mi], acc[mi][ni], 0, 0, 0);
;     asm volatile("s_waitcnt lgkmcnt(0)" : "+v"(ag[0]), "+v"(ag[1]), "+v"(ag[2]), "+v"(ag[3]), "+v"(bg[0]), "+v"(bg[1]), "+v"(bg[2]), "+v"(bg[3]) :: "memory");
; #pragma unroll
;     for (int mi = 0; mi < 4; ++mi)
; #pragma unroll
;       for (int ni = 0; ni < 4; ++ni) acc[mi][ni] = __builtin_amdgcn_mfma_f32_16x16x32_bf16(bg[ni], ag[mi], acc[mi][ni], 0, 0, 0);
	v_mfma_f32_16x16x32_bf16 v[92:95], v[22:25], v[2:5], 0
	v_add_u32_e32 v85, 0x8000, v82
	v_or_b32_e32 v87, 0xc000, v87
	v_mfma_f32_16x16x32_bf16 v[96:99], v[26:29], v[2:5], 0
	s_add_u32 s0, s54, s0
	s_addc_u32 s1, s55, s1
	s_add_u32 s2, s76, s2
	v_mfma_f32_16x16x32_bf16 v[100:103], v[30:33], v[2:5], 0
	s_addc_u32 s3, s77, s3
	s_add_i32 s38, s38, 1
	s_add_i32 s39, s39, s49
	v_mfma_f32_16x16x32_bf16 v[108:111], v[18:21], v[6:9], 0
	v_mfma_f32_16x16x32_bf16 v[112:115], v[22:25], v[6:9], 0
	v_mfma_f32_16x16x32_bf16 v[116:119], v[26:29], v[6:9], 0
	v_mfma_f32_16x16x32_bf16 v[120:123], v[30:33], v[6:9], 0
	v_mfma_f32_16x16x32_bf16 v[124:127], v[18:21], v[10:13], 0
	v_mfma_f32_16x16x32_bf16 v[128:131], v[22:25], v[10:13], 0
	v_mfma_f32_16x16x32_bf16 v[132:135], v[26:29], v[10:13], 0
	s_waitcnt vmcnt(0)
	v_mfma_f32_16x16x32_bf16 v[140:143], v[30:33], v[10:13], 0
	v_mfma_f32_16x16x32_bf16 v[144:147], v[18:21], v[14:17], 0
	v_mfma_f32_16x16x32_bf16 v[148:151], v[22:25], v[14:17], 0
	v_mfma_f32_16x16x32_bf16 v[152:155], v[26:29], v[14:17], 0
	v_mfma_f32_16x16x32_bf16 v[156:159], v[30:33], v[14:17], 0
	v_mfma_f32_16x16x32_bf16 v[2:5], v[50:53], v[34:37], v[42:45]
	v_mfma_f32_16x16x32_bf16 v[6:9], v[54:57], v[34:37], v[92:95]
	v_mfma_f32_16x16x32_bf16 v[10:13], v[58:61], v[34:37], v[96:99]
	v_mfma_f32_16x16x32_bf16 v[14:17], v[88:91], v[34:37], v[100:103]
	v_mfma_f32_16x16x32_bf16 v[18:21], v[50:53], v[38:41], v[108:111]
	v_mfma_f32_16x16x32_bf16 v[22:25], v[54:57], v[38:41], v[112:115]
	v_mfma_f32_16x16x32_bf16 v[26:29], v[58:61], v[38:41], v[116:119]
	v_mfma_f32_16x16x32_bf16 v[30:33], v[88:91], v[38:41], v[120:123]
	v_mfma_f32_16x16x32_bf16 v[34:37], v[50:53], v[46:49], v[124:127]
	v_mfma_f32_16x16x32_bf16 v[38:41], v[54:57], v[46:49], v[128:131]
	v_mfma_f32_16x16x32_bf16 v[42:45], v[58:61], v[46:49], v[132:135]
	v_mfma_f32_16x16x32_bf16 v[46:49], v[88:91], v[46:49], v[140:143]
	v_mfma_f32_16x16x32_bf16 v[50:53], v[50:53], v[62:65], v[144:147]
	v_mfma_f32_16x16x32_bf16 v[54:57], v[54:57], v[62:65], v[148:151]
	v_mfma_f32_16x16x32_bf16 v[58:61], v[58:61], v[62:65], v[152:155]
	v_mfma_f32_16x16x32_bf16 v[62:65], v[88:91], v[62:65], v[156:159]
	v_lshl_add_u64 v[88:89], v[80:81], 0, s[70:71]
	global_load_lds_dwordx4 v[88:89], off
	v_lshl_add_u64 v[88:89], v[78:79], 0, s[70:71]
	s_mov_b32 m0, s41
	s_nop 0
	global_load_lds_dwordx4 v[88:89], off
	v_lshl_add_u64 v[88:89], v[76:77], 0, s[70:71]
	s_mov_b32 m0, s44
	s_nop 0
	global_load_lds_dwordx4 v[88:89], off
	v_lshl_add_u64 v[88:89], v[74:75], 0, s[70:71]
	s_mov_b32 m0, s45
	s_nop 0
	global_load_lds_dwordx4 v[88:89], off
	v_lshl_add_u64 v[88:89], v[72:73], 0, s[70:71]
	s_mov_b32 m0, s46
	s_nop 0
	global_load_lds_dwordx4 v[88:89], off
	v_lshl_add_u64 v[88:89], v[70:71], 0, s[70:71]
	s_mov_b32 m0, s42
	s_nop 0
	global_load_lds_dwordx4 v[88:89], off
	v_lshl_add_u64 v[88:89], v[68:69], 0, s[70:71]
	s_mov_b32 m0, s43
	s_nop 0
	global_load_lds_dwordx4 v[88:89], off
	v_lshl_add_u64 v[88:89], v[66:67], 0, s[70:71]
	s_mov_b32 m0, s31
	s_nop 0
	global_load_lds_dwordx4 v[88:89], off
	v_or_b32_e32 v88, 0xc000, v86
	ds_read_b128 v[90:93], v85
	ds_read_b128 v[94:97], v85 offset:2048
	ds_read_b128 v[98:101], v85 offset:4096
	ds_read_b128 v[102:105], v85 offset:6144
	ds_read_b128 v[108:111], v88
	ds_read_b128 v[112:115], v88 offset:2048
	ds_read_b128 v[116:119], v88 offset:4096
	ds_read_b128 v[120:123], v88 offset:6144
	v_add_u32_e32 v86, 0x8000, v0
	ds_read_b128 v[124:127], v86
	ds_read_b128 v[128:131], v86 offset:2048
	ds_read_b128 v[132:135], v86 offset:4096
	ds_read_b128 v[140:143], v86 offset:6144
	ds_read_b128 v[144:147], v87
	ds_read_b128 v[148:151], v87 offset:2048
	ds_read_b128 v[152:155], v87 offset:4096
	ds_read_b128 v[156:159], v87 offset:6144
	s_waitcnt lgkmcnt(8)
	s_mov_b32 m0, s21
	s_waitcnt lgkmcnt(0)
	v_mfma_f32_16x16x32_bf16 v[2:5], v[108:111], v[90:93], v[2:5]
	s_waitcnt vmcnt(0)
	s_barrier
	v_mfma_f32_16x16x32_bf16 v[6:9], v[112:115], v[90:93], v[6:9]
	v_mfma_f32_16x16x32_bf16 v[10:13], v[116:119], v[90:93], v[10:13]
	v_mfma_f32_16x16x32_bf16 v[14:17], v[120:123], v[90:93], v[14:17]
	v_lshl_add_u64 v[90:91], v[80:81], 0, s[72:73]
	global_load_lds_dwordx4 v[90:91], off
	v_lshl_add_u64 v[90:91], v[78:79], 0, s[72:73]
	s_mov_b32 m0, s20
	v_mfma_f32_16x16x32_bf16 v[18:21], v[108:111], v[94:97], v[18:21]
	global_load_lds_dwordx4 v[90:91], off
	v_lshl_add_u64 v[90:91], v[76:77], 0, s[72:73]
	s_mov_b32 m0, s23
	v_mfma_f32_16x16x32_bf16 v[22:25], v[112:115], v[94:97], v[22:25]
	global_load_lds_dwordx4 v[90:91], off
	v_lshl_add_u64 v[90:91], v[74:75], 0, s[72:73]
	s_mov_b32 m0, s25
	v_mfma_f32_16x16x32_bf16 v[26:29], v[116:119], v[94:97], v[26:29]
	global_load_lds_dwordx4 v[90:91], off
	v_lshl_add_u64 v[90:91], v[72:73], 0, s[72:73]
	s_mov_b32 m0, s26
	v_mfma_f32_16x16x32_bf16 v[30:33], v[120:123], v[94:97], v[30:33]
	global_load_lds_dwordx4 v[90:91], off
	v_lshl_add_u64 v[90:91], v[70:71], 0, s[72:73]
	s_mov_b32 m0, s27
	v_mfma_f32_16x16x32_bf16 v[34:37], v[108:111], v[98:101], v[34:37]
	global_load_lds_dwordx4 v[90:91], off
	v_lshl_add_u64 v[90:91], v[68:69], 0, s[72:73]
	v_mfma_f32_16x16x32_bf16 v[38:41], v[112:115], v[98:101], v[38:41]
	s_mov_b32 m0, s30
	s_nop 0
	global_load_lds_dwordx4 v[90:91], off
	v_mfma_f32_16x16x32_bf16 v[42:45], v[116:119], v[98:101], v[42:45]
	v_lshl_add_u64 v[90:91], v[66:67], 0, s[72:73]
	s_mov_b32 m0, s47
	v_mfma_f32_16x16x32_bf16 v[46:49], v[120:123], v[98:101], v[46:49]
	global_load_lds_dwordx4 v[90:91], off
	s_mov_b32 m0, s40
	v_mfma_f32_16x16x32_bf16 v[50:53], v[108:111], v[102:105], v[50:53]
	v_mfma_f32_16x16x32_bf16 v[54:57], v[112:115], v[102:105], v[54:57]
; DI void gemm_dma(f32x4 (&acc)[4][4], const bf16_t* Ap, int lda, const bf16_t* Bp, int ldb, int K, char* lds) {
;     ...
;   for (int kt = 0; kt < nk; ++kt) {
;     asm volatile("s_waitcnt vmcnt(0)" ::: "memory");
;     __builtin_amdgcn_s_barrier();
;     asm volatile("" ::: "memory");
;     if (kt + 1 < nk) issue(kt + 1);
;     const unsigned sa = lbase + (unsigned)((kt & 1) * 32768);
;     bf16x8 af[4], bfr[4], ag[4], bg[4];
;     asm volatile("ds_read_b128 %0, %8\n\tds_read_b128 %1, %8 offset:2048\n\tds_read_b128 %2, %8 offset:4096\n\tds_read_b128 %3, %8 offset:6144\n\t"
;                  "ds_read_b128 %4, %9\n\tds_read_b128 %5, %9 offset:2048\n\tds_read_b128 %6, %9 offset:4096\n\tds_read_b128 %7, %9 offset:6144"
;                  : "=&v"(af[0]), "=&v"(af[1]), "=&v"(af[2]), "=&v"(af[3]), "=&v"(bfr[0]), "=&v"(bfr[1]), "=&v"(bfr[2]), "=&v"(bfr[3])
;                  : "v"(sa + a0), "v"(sa + b0) : "memory");
;     asm volatile("ds_read_b128 %0, %16\n\tds_read_b128 %1, %16 offset:2048\n\tds_read_b128 %2, %16 offset:4096\n\tds_read_b128 %3, %16 offset:6144\n\t"
;                  "ds_read_b128 %4, %17\n\tds_read_b128 %5, %17 offset:2048\n\tds_read_b128 %6, %17 offset:4096\n\tds_read_b128 %7, %17 offset:6144\n\t"
;                  "s_waitcnt lgkmcnt(8)"
;                  : "=&v"(ag[0]), "=&v"(ag[1]), "=&v"(ag[2]), "=&v"(ag[3]), "=&v"(bg[0]), "=&v"(bg[1]), "=&v"(bg[2]), "=&v"(bg[3]),
;                    "+v"(af[0]), "+v"(af[1]), "+v"(af[2]), "+v"(af[3]), "+v"(bfr[0]), "+v"(bfr[1]), "+v"(bfr[2]), "+v"(bfr[3])
;                  : "v"(sa + a1), "v"(sa + b1) : "memory");
; #pragma unroll
;     for (int mi = 0; mi < 4; ++mi)
; #pragma unroll
;       for (int ni = 0; ni < 4; ++ni) acc[mi][ni] = __builtin_amdgcn_mfma_f32_16x16x32_bf16(bfr[ni], af[mi], acc[mi][ni], 0, 0, 0);
;     asm volatile("s_waitcnt lgkmcnt(0)" : "+v"(ag[0]), "+v"(ag[1]), "+v"(ag[2]), "+v"(ag[3]), "+v"(bg[0]), "+v"(bg[1]), "+v"(bg[2]), "+v"(bg[3]) :: "memory");
; #pragma unroll
;     for (int mi = 0; mi < 4; ++mi)
; #pragma unroll
;       for (int ni = 0; ni < 4; ++ni) acc[mi][ni] = __builtin_amdgcn_mfma_f32_16x16x32_bf16(bg[ni], ag[mi], acc[mi][ni], 0, 0, 0);
	v_mfma_f32_16x16x32_bf16 v[58:61], v[116:119], v[102:105], v[58:61]
	v_mfma_f32_16x16x32_bf16 v[62:65], v[120:123], v[102:105], v[62:65]
	ds_read_b128 v[90:93], v82
	ds_read_b128 v[94:97], v82 offset:2048
	ds_read_b128 v[98:101], v82 offset:4096
	ds_read_b128 v[102:105], v82 offset:6144
	ds_read_b128 v[108:111], v84
	ds_read_b128 v[112:115], v84 offset:2048
	ds_read_b128 v[116:119], v84 offset:4096
	ds_read_b128 v[120:123], v84 offset:6144
	v_mfma_f32_16x16x32_bf16 v[2:5], v[144:147], v[124:127], v[2:5]
	v_mfma_f32_16x16x32_bf16 v[6:9], v[148:151], v[124:127], v[6:9]
	v_mfma_f32_16x16x32_bf16 v[10:13], v[152:155], v[124:127], v[10:13]
	v_mfma_f32_16x16x32_bf16 v[14:17], v[156:159], v[124:127], v[14:17]
	v_mfma_f32_16x16x32_bf16 v[18:21], v[144:147], v[128:131], v[18:21]
	v_mfma_f32_16x16x32_bf16 v[22:25], v[148:151], v[128:131], v[22:25]
	v_mfma_f32_16x16x32_bf16 v[26:29], v[152:155], v[128:131], v[26:29]
	v_mfma_f32_16x16x32_bf16 v[30:33], v[156:159], v[128:131], v[30:33]
	v_mfma_f32_16x16x32_bf16 v[34:37], v[144:147], v[132:135], v[34:37]
	v_mfma_f32_16x16x32_bf16 v[38:41], v[148:151], v[132:135], v[38:41]
	v_mfma_f32_16x16x32_bf16 v[42:45], v[152:155], v[132:135], v[42:45]
	v_mfma_f32_16x16x32_bf16 v[46:49], v[156:159], v[132:135], v[46:49]
	v_mfma_f32_16x16x32_bf16 v[50:53], v[144:147], v[140:143], v[50:53]
	v_mfma_f32_16x16x32_bf16 v[54:57], v[148:151], v[140:143], v[54:57]
	v_mfma_f32_16x16x32_bf16 v[58:61], v[152:155], v[140:143], v[58:61]
	v_mfma_f32_16x16x32_bf16 v[62:65], v[156:159], v[140:143], v[62:65]
	ds_read_b128 v[124:127], v0
	ds_read_b128 v[128:131], v0 offset:2048
	ds_read_b128 v[132:135], v0 offset:4096
	ds_read_b128 v[140:143], v0 offset:6144
	ds_read_b128 v[144:147], v83
	ds_read_b128 v[148:151], v83 offset:2048
	ds_read_b128 v[152:155], v83 offset:4096
	ds_read_b128 v[156:159], v83 offset:6144
	s_waitcnt lgkmcnt(8)
	s_nop 0
	s_waitcnt lgkmcnt(0)
	v_mfma_f32_16x16x32_bf16 v[2:5], v[108:111], v[90:93], v[2:5]
	s_waitcnt vmcnt(0)
	s_barrier
	v_mfma_f32_16x16x32_bf16 v[6:9], v[112:115], v[90:93], v[6:9]
	v_mfma_f32_16x16x32_bf16 v[10:13], v[116:119], v[90:93], v[10:13]
	v_mfma_f32_16x16x32_bf16 v[14:17], v[120:123], v[90:93], v[14:17]
	v_lshl_add_u64 v[90:91], v[80:81], 0, s[68:69]
	global_load_lds_dwordx4 v[90:91], off
	v_lshl_add_u64 v[90:91], v[78:79], 0, s[68:69]
	s_mov_b32 m0, s41
	v_mfma_f32_16x16x32_bf16 v[18:21], v[108:111], v[94:97], v[18:21]
	global_load_lds_dwordx4 v[90:91], off
	v_lshl_add_u64 v[90:91], v[76:77], 0, s[68:69]
	s_mov_b32 m0, s44
	v_mfma_f32_16x16x32_bf16 v[22:25], v[112:115], v[94:97], v[22:25]
	global_load_lds_dwordx4 v[90:91], off
	v_lshl_add_u64 v[90:91], v[74:75], 0, s[68:69]
	s_mov_b32 m0, s45
	v_mfma_f32_16x16x32_bf16 v[26:29], v[116:119], v[94:97], v[26:29]
	global_load_lds_dwordx4 v[90:91], off
	v_lshl_add_u64 v[90:91], v[72:73], 0, s[68:69]
	s_mov_b32 m0, s46
	v_mfma_f32_16x16x32_bf16 v[30:33], v[120:123], v[94:97], v[30:33]
	global_load_lds_dwordx4 v[90:91], off
	v_lshl_add_u64 v[90:91], v[70:71], 0, s[68:69]
	s_mov_b32 m0, s42
	v_mfma_f32_16x16x32_bf16 v[34:37], v[108:111], v[98:101], v[34:37]
	global_load_lds_dwordx4 v[90:91], off
	v_lshl_add_u64 v[90:91], v[68:69], 0, s[68:69]
	v_mfma_f32_16x16x32_bf16 v[38:41], v[112:115], v[98:101], v[38:41]
	s_mov_b32 m0, s43
	s_nop 0
	global_load_lds_dwordx4 v[90:91], off
	v_mfma_f32_16x16x32_bf16 v[42:45], v[116:119], v[98:101], v[42:45]
	v_lshl_add_u64 v[90:91], v[66:67], 0, s[68:69]
	s_mov_b32 m0, s31
	v_mfma_f32_16x16x32_bf16 v[46:49], v[120:123], v[98:101], v[46:49]
	global_load_lds_dwordx4 v[90:91], off
	s_mov_b32 m0, s21
	v_mfma_f32_16x16x32_bf16 v[50:53], v[108:111], v[102:105], v[50:53]
	v_mfma_f32_16x16x32_bf16 v[54:57], v[112:115], v[102:105], v[54:57]
	v_mfma_f32_16x16x32_bf16 v[58:61], v[116:119], v[102:105], v[58:61]
	v_mfma_f32_16x16x32_bf16 v[62:65], v[120:123], v[102:105], v[62:65]
	ds_read_b128 v[90:93], v85
	ds_read_b128 v[94:97], v85 offset:2048
	ds_read_b128 v[98:101], v85 offset:4096
	ds_read_b128 v[102:105], v85 offset:6144
	ds_read_b128 v[108:111], v88
	ds_read_b128 v[112:115], v88 offset:2048
	ds_read_b128 v[116:119], v88 offset:4096
	ds_read_b128 v[120:123], v88 offset:6144
	v_mfma_f32_16x16x32_bf16 v[2:5], v[144:147], v[124:127], v[2:5]
	v_mfma_f32_16x16x32_bf16 v[6:9], v[148:151], v[124:127], v[6:9]
	v_mfma_f32_16x16x32_bf16 v[10:13], v[152:155], v[124:127], v[10:13]
	v_mfma_f32_16x16x32_bf16 v[14:17], v[156:159], v[124:127], v[14:17]
	v_mfma_f32_16x16x32_bf16 v[18:21], v[144:147], v[128:131], v[18:21]
	v_mfma_f32_16x16x32_bf16 v[22:25], v[148:151], v[128:131], v[22:25]
	v_mfma_f32_16x16x32_bf16 v[26:29], v[152:155], v[128:131], v[26:29]
	v_mfma_f32_16x16x32_bf16 v[30:33], v[156:159], v[128:131], v[30:33]
	v_mfma_f32_16x16x32_bf16 v[34:37], v[144:147], v[132:135], v[34:37]
	v_mfma_f32_16x16x32_bf16 v[38:41], v[148:151], v[132:135], v[38:41]
	v_mfma_f32_16x16x32_bf16 v[42:45], v[152:155], v[132:135], v[42:45]
	v_mfma_f32_16x16x32_bf16 v[46:49], v[156:159], v[132:135], v[46:49]
	v_mfma_f32_16x16x32_bf16 v[50:53], v[144:147], v[140:143], v[50:53]
	v_mfma_f32_16x16x32_bf16 v[54:57], v[148:151], v[140:143], v[54:57]
	v_mfma_f32_16x16x32_bf16 v[58:61], v[152:155], v[140:143], v[58:61]
	v_mfma_f32_16x16x32_bf16 v[62:65], v[156:159], v[140:143], v[62:65]
	ds_read_b128 v[124:127], v86
	ds_read_b128 v[128:131], v86 offset:2048
	ds_read_b128 v[132:135], v86 offset:4096
	ds_read_b128 v[140:143], v86 offset:6144
	ds_read_b128 v[144:147], v87
	ds_read_b128 v[148:151], v87 offset:2048
	ds_read_b128 v[152:155], v87 offset:4096
	ds_read_b128 v[156:159], v87 offset:6144
	s_waitcnt lgkmcnt(8)
	s_nop 0
	s_waitcnt lgkmcnt(0)
	v_mfma_f32_16x16x32_bf16 v[2:5], v[108:111], v[90:93], v[2:5]
	s_waitcnt vmcnt(0)
	s_barrier
; DI void gemm_dma(f32x4 (&acc)[4][4], const bf16_t* Ap, int lda, const bf16_t* Bp, int ldb, int K, char* lds) {
;     ...
;   for (int kt = 0; kt < nk; ++kt) {
;     asm volatile("s_waitcnt vmcnt(0)" ::: "memory");
;     __builtin_amdgcn_s_barrier();
;     asm volatile("" ::: "memory");
;     if (kt + 1 < nk) issue(kt + 1);
;     const unsigned sa = lbase + (unsigned)((kt & 1) * 32768);
;     bf16x8 af[4], bfr[4], ag[4], bg[4];
;     asm volatile("ds_read_b128 %0, %8\n\tds_read_b128 %1, %8 offset:2048\n\tds_read_b128 %2, %8 offset:4096\n\tds_read_b128 %3, %8 offset:6144\n\t"
;                  "ds_read_b128 %4, %9\n\tds_read_b128 %5, %9 offset:2048\n\tds_read_b128 %6, %9 offset:4096\n\tds_read_b128 %7, %9 offset:6144"
;                  : "=&v"(af[0]), "=&v"(af[1]), "=&v"(af[2]), "=&v"(af[3]), "=&v"(bfr[0]), "=&v"(bfr[1]), "=&v"(bfr[2]), "=&v"(bfr[3])
;                  : "v"(sa + a0), "v"(sa + b0) : "memory");
;     asm volatile("ds_read_b128 %0, %16\n\tds_read_b128 %1, %16 offset:2048\n\tds_read_b128 %2, %16 offset:4096\n\tds_read_b128 %3, %16 offset:6144\n\t"
;                  "ds_read_b128 %4, %17\n\tds_read_b128 %5, %17 offset:2048\n\tds_read_b128 %6, %17 offset:4096\n\tds_read_b128 %7, %17 offset:6144\n\t"
;                  "s_waitcnt lgkmcnt(8)"
;                  : "=&v"(ag[0]), "=&v"(ag[1]), "=&v"(ag[2]), "=&v"(ag[3]), "=&v"(bg[0]), "=&v"(bg[1]), "=&v"(bg[2]), "=&v"(bg[3]),
;                    "+v"(af[0]), "+v"(af[1]), "+v"(af[2]), "+v"(af[3]), "+v"(bfr[0]), "+v"(bfr[1]), "+v"(bfr[2]), "+v"(bfr[3])
;                  : "v"(sa + a1), "v"(sa + b1) : "memory");
; #pragma unroll
;     for (int mi = 0; mi < 4; ++mi)
; #pragma unroll
;       for (int ni = 0; ni < 4; ++ni) acc[mi][ni] = __builtin_amdgcn_mfma_f32_16x16x32_bf16(bfr[ni], af[mi], acc[mi][ni], 0, 0, 0);
;     asm volatile("s_waitcnt lgkmcnt(0)" : "+v"(ag[0]), "+v"(ag[1]), "+v"(ag[2]), "+v"(ag[3]), "+v"(bg[0]), "+v"(bg[1]), "+v"(bg[2]), "+v"(bg[3]) :: "memory");
; #pragma unroll
;     for (int mi = 0; mi < 4; ++mi)
; #pragma unroll
;       for (int ni = 0; ni < 4; ++ni) acc[mi][ni] = __builtin_amdgcn_mfma_f32_16x16x32_bf16(bg[ni], ag[mi], acc[mi][ni], 0, 0, 0);
	v_mfma_f32_16x16x32_bf16 v[6:9], v[112:115], v[90:93], v[6:9]
	v_mfma_f32_16x16x32_bf16 v[10:13], v[116:119], v[90:93], v[10:13]
	v_mfma_f32_16x16x32_bf16 v[14:17], v[120:123], v[90:93], v[14:17]
	v_lshl_add_u64 v[90:91], v[80:81], 0, s[78:79]
	global_load_lds_dwordx4 v[90:91], off
	v_lshl_add_u64 v[90:91], v[78:79], 0, s[78:79]
	s_mov_b32 m0, s20
	v_mfma_f32_16x16x32_bf16 v[18:21], v[108:111], v[94:97], v[18:21]
	global_load_lds_dwordx4 v[90:91], off
	v_lshl_add_u64 v[90:91], v[76:77], 0, s[78:79]
	s_mov_b32 m0, s23
	v_mfma_f32_16x16x32_bf16 v[22:25], v[112:115], v[94:97], v[22:25]
	global_load_lds_dwordx4 v[90:91], off
	v_lshl_add_u64 v[90:91], v[74:75], 0, s[78:79]
	s_mov_b32 m0, s25
	v_mfma_f32_16x16x32_bf16 v[26:29], v[116:119], v[94:97], v[26:29]
	global_load_lds_dwordx4 v[90:91], off
	v_lshl_add_u64 v[90:91], v[72:73], 0, s[78:79]
	s_mov_b32 m0, s26
	v_mfma_f32_16x16x32_bf16 v[30:33], v[120:123], v[94:97], v[30:33]
	global_load_lds_dwordx4 v[90:91], off
	v_lshl_add_u64 v[90:91], v[70:71], 0, s[78:79]
	s_mov_b32 m0, s27
	v_mfma_f32_16x16x32_bf16 v[34:37], v[108:111], v[98:101], v[34:37]
	global_load_lds_dwordx4 v[90:91], off
	v_lshl_add_u64 v[90:91], v[68:69], 0, s[78:79]
	v_mfma_f32_16x16x32_bf16 v[38:41], v[112:115], v[98:101], v[38:41]
	s_mov_b32 m0, s30
	s_nop 0
	global_load_lds_dwordx4 v[90:91], off
	v_mfma_f32_16x16x32_bf16 v[42:45], v[116:119], v[98:101], v[42:45]
	v_lshl_add_u64 v[90:91], v[66:67], 0, s[78:79]
	s_mov_b32 m0, s47
	v_mfma_f32_16x16x32_bf16 v[46:49], v[120:123], v[98:101], v[46:49]
	global_load_lds_dwordx4 v[90:91], off
	s_mov_b32 m0, s40
	v_mfma_f32_16x16x32_bf16 v[50:53], v[108:111], v[102:105], v[50:53]
	v_mfma_f32_16x16x32_bf16 v[54:57], v[112:115], v[102:105], v[54:57]
	v_mfma_f32_16x16x32_bf16 v[58:61], v[116:119], v[102:105], v[58:61]
	v_mfma_f32_16x16x32_bf16 v[62:65], v[120:123], v[102:105], v[62:65]
	ds_read_b128 v[90:93], v82
	ds_read_b128 v[94:97], v82 offset:2048
	ds_read_b128 v[98:101], v82 offset:4096
	ds_read_b128 v[102:105], v82 offset:6144
	ds_read_b128 v[108:111], v84
	ds_read_b128 v[112:115], v84 offset:2048
	ds_read_b128 v[116:119], v84 offset:4096
	ds_read_b128 v[120:123], v84 offset:6144
	v_mfma_f32_16x16x32_bf16 v[2:5], v[144:147], v[124:127], v[2:5]
	v_mfma_f32_16x16x32_bf16 v[6:9], v[148:151], v[124:127], v[6:9]
	v_mfma_f32_16x16x32_bf16 v[10:13], v[152:155], v[124:127], v[10:13]
	v_mfma_f32_16x16x32_bf16 v[14:17], v[156:159], v[124:127], v[14:17]
	v_mfma_f32_16x16x32_bf16 v[18:21], v[144:147], v[128:131], v[18:21]
	v_mfma_f32_16x16x32_bf16 v[22:25], v[148:151], v[128:131], v[22:25]
	v_mfma_f32_16x16x32_bf16 v[26:29], v[152:155], v[128:131], v[26:29]
	v_mfma_f32_16x16x32_bf16 v[30:33], v[156:159], v[128:131], v[30:33]
	v_mfma_f32_16x16x32_bf16 v[34:37], v[144:147], v[132:135], v[34:37]
	v_mfma_f32_16x16x32_bf16 v[38:41], v[148:151], v[132:135], v[38:41]
	v_mfma_f32_16x16x32_bf16 v[42:45], v[152:155], v[132:135], v[42:45]
	v_mfma_f32_16x16x32_bf16 v[46:49], v[156:159], v[132:135], v[46:49]
	v_mfma_f32_16x16x32_bf16 v[50:53], v[144:147], v[140:143], v[50:53]
	v_mfma_f32_16x16x32_bf16 v[54:57], v[148:151], v[140:143], v[54:57]
	v_mfma_f32_16x16x32_bf16 v[58:61], v[152:155], v[140:143], v[58:61]
	v_mfma_f32_16x16x32_bf16 v[62:65], v[156:159], v[140:143], v[62:65]
	ds_read_b128 v[124:127], v0
	ds_read_b128 v[128:131], v0 offset:2048
	ds_read_b128 v[132:135], v0 offset:4096
	ds_read_b128 v[140:143], v0 offset:6144
	ds_read_b128 v[144:147], v83
	ds_read_b128 v[148:151], v83 offset:2048
	ds_read_b128 v[152:155], v83 offset:4096
	ds_read_b128 v[156:159], v83 offset:6144
	s_waitcnt lgkmcnt(8)
	s_nop 0
	s_waitcnt lgkmcnt(0)
	v_mfma_f32_16x16x32_bf16 v[2:5], v[108:111], v[90:93], v[2:5]
	s_waitcnt vmcnt(0)
	s_barrier
	v_mfma_f32_16x16x32_bf16 v[6:9], v[112:115], v[90:93], v[6:9]
	v_mfma_f32_16x16x32_bf16 v[10:13], v[116:119], v[90:93], v[10:13]
	v_mfma_f32_16x16x32_bf16 v[14:17], v[120:123], v[90:93], v[14:17]
	v_lshl_add_u64 v[90:91], v[80:81], 0, s[80:81]
	global_load_lds_dwordx4 v[90:91], off
	v_lshl_add_u64 v[90:91], v[78:79], 0, s[80:81]
	s_mov_b32 m0, s41
	v_mfma_f32_16x16x32_bf16 v[18:21], v[108:111], v[94:97], v[18:21]
	global_load_lds_dwordx4 v[90:91], off
	v_lshl_add_u64 v[90:91], v[76:77], 0, s[80:81]
	s_mov_b32 m0, s44
	v_mfma_f32_16x16x32_bf16 v[22:25], v[112:115], v[94:97], v[22:25]
	global_load_lds_dwordx4 v[90:91], off
	v_lshl_add_u64 v[90:91], v[74:75], 0, s[80:81]
	s_mov_b32 m0, s45
	v_mfma_f32_16x16x32_bf16 v[26:29], v[116:119], v[94:97], v[26:29]
	global_load_lds_dwordx4 v[90:91], off
	v_lshl_add_u64 v[90:91], v[72:73], 0, s[80:81]
	s_mov_b32 m0, s46
	v_mfma_f32_16x16x32_bf16 v[30:33], v[120:123], v[94:97], v[30:33]
	global_load_lds_dwordx4 v[90:91], off
	v_lshl_add_u64 v[90:91], v[70:71], 0, s[80:81]
	s_mov_b32 m0, s42
	v_mfma_f32_16x16x32_bf16 v[34:37], v[108:111], v[98:101], v[34:37]
	global_load_lds_dwordx4 v[90:91], off
	v_lshl_add_u64 v[90:91], v[68:69], 0, s[80:81]
	v_mfma_f32_16x16x32_bf16 v[38:41], v[112:115], v[98:101], v[38:41]
	s_mov_b32 m0, s43
	v_lshl_add_u64 v[80:81], v[80:81], 0, s[88:89]
	global_load_lds_dwordx4 v[90:91], off
	v_mfma_f32_16x16x32_bf16 v[42:45], v[116:119], v[98:101], v[42:45]
	v_lshl_add_u64 v[90:91], v[66:67], 0, s[80:81]
	s_mov_b32 m0, s31
	v_lshl_add_u64 v[78:79], v[78:79], 0, s[88:89]
	v_mfma_f32_16x16x32_bf16 v[46:49], v[120:123], v[98:101], v[46:49]
	global_load_lds_dwordx4 v[90:91], off
	s_mov_b32 m0, s21
	v_mfma_f32_16x16x32_bf16 v[50:53], v[108:111], v[102:105], v[50:53]
	v_lshl_add_u64 v[76:77], v[76:77], 0, s[88:89]
	v_lshl_add_u64 v[74:75], v[74:75], 0, s[88:89]
	v_lshl_add_u64 v[72:73], v[72:73], 0, s[88:89]
; DI void gemm_dma(f32x4 (&acc)[4][4], const bf16_t* Ap, int lda, const bf16_t* Bp, int ldb, int K, char* lds) {
;     ...
;   for (int kt = 0; kt < nk; ++kt) {
;     asm volatile("s_waitcnt vmcnt(0)" ::: "memory");
;     __builtin_amdgcn_s_barrier();
;     asm volatile("" ::: "memory");
;     if (kt + 1 < nk) issue(kt + 1);
;     const unsigned sa = lbase + (unsigned)((kt & 1) * 32768);
;     bf16x8 af[4], bfr[4], ag[4], bg[4];
;     asm volatile("ds_read_b128 %0, %8\n\tds_read_b128 %1, %8 offset:2048\n\tds_read_b128 %2, %8 offset:4096\n\tds_read_b128 %3, %8 offset:6144\n\t"
;                  "ds_read_b128 %4, %9\n\tds_read_b128 %5, %9 offset:2048\n\tds_read_b128 %6, %9 offset:4096\n\tds_read_b128 %7, %9 offset:6144"
;                  : "=&v"(af[0]), "=&v"(af[1]), "=&v"(af[2]), "=&v"(af[3]), "=&v"(bfr[0]), "=&v"(bfr[1]), "=&v"(bfr[2]), "=&v"(bfr[3])
;                  : "v"(sa + a0), "v"(sa + b0) : "memory");
;     asm volatile("ds_read_b128 %0, %16\n\tds_read_b128 %1, %16 offset:2048\n\tds_read_b128 %2, %16 offset:4096\n\tds_read_b128 %3, %16 offset:6144\n\t"
;                  "ds_read_b128 %4, %17\n\tds_read_b128 %5, %17 offset:2048\n\tds_read_b128 %6, %17 offset:4096\n\tds_read_b128 %7, %17 offset:6144\n\t"
;                  "s_waitcnt lgkmcnt(8)"
;                  : "=&v"(ag[0]), "=&v"(ag[1]), "=&v"(ag[2]), "=&v"(ag[3]), "=&v"(bg[0]), "=&v"(bg[1]), "=&v"(bg[2]), "=&v"(bg[3]),
;                    "+v"(af[0]), "+v"(af[1]), "+v"(af[2]), "+v"(af[3]), "+v"(bfr[0]), "+v"(bfr[1]), "+v"(bfr[2]), "+v"(bfr[3])
;                  : "v"(sa + a1), "v"(sa + b1) : "memory");
; #pragma unroll
;     for (int mi = 0; mi < 4; ++mi)
; #pragma unroll
;       for (int ni = 0; ni < 4; ++ni) acc[mi][ni] = __builtin_amdgcn_mfma_f32_16x16x32_bf16(bfr[ni], af[mi], acc[mi][ni], 0, 0, 0);
;     asm volatile("s_waitcnt lgkmcnt(0)" : "+v"(ag[0]), "+v"(ag[1]), "+v"(ag[2]), "+v"(ag[3]), "+v"(bg[0]), "+v"(bg[1]), "+v"(bg[2]), "+v"(bg[3]) :: "memory");
; #pragma unroll
;     for (int mi = 0; mi < 4; ++mi)
; #pragma unroll
;       for (int ni = 0; ni < 4; ++ni) acc[mi][ni] = __builtin_amdgcn_mfma_f32_16x16x32_bf16(bg[ni], ag[mi], acc[mi][ni], 0, 0, 0);
;   }
	v_mfma_f32_16x16x32_bf16 v[54:57], v[112:115], v[102:105], v[54:57]
	v_lshl_add_u64 v[70:71], v[70:71], 0, s[88:89]
	v_lshl_add_u64 v[68:69], v[68:69], 0, s[88:89]
	v_lshl_add_u64 v[66:67], v[66:67], 0, s[88:89]
	v_mfma_f32_16x16x32_bf16 v[58:61], v[116:119], v[102:105], v[58:61]
	v_mfma_f32_16x16x32_bf16 v[62:65], v[120:123], v[102:105], v[62:65]
	ds_read_b128 v[90:93], v85
	ds_read_b128 v[94:97], v85 offset:2048
	ds_read_b128 v[98:101], v85 offset:4096
	ds_read_b128 v[102:105], v85 offset:6144
	ds_read_b128 v[108:111], v88
	ds_read_b128 v[112:115], v88 offset:2048
	ds_read_b128 v[116:119], v88 offset:4096
	ds_read_b128 v[120:123], v88 offset:6144
	v_mfma_f32_16x16x32_bf16 v[2:5], v[144:147], v[124:127], v[2:5]
	v_mfma_f32_16x16x32_bf16 v[6:9], v[148:151], v[124:127], v[6:9]
	v_mfma_f32_16x16x32_bf16 v[10:13], v[152:155], v[124:127], v[10:13]
	v_mfma_f32_16x16x32_bf16 v[14:17], v[156:159], v[124:127], v[14:17]
	v_mfma_f32_16x16x32_bf16 v[18:21], v[144:147], v[128:131], v[18:21]
	v_mfma_f32_16x16x32_bf16 v[22:25], v[148:151], v[128:131], v[22:25]
	v_mfma_f32_16x16x32_bf16 v[26:29], v[152:155], v[128:131], v[26:29]
	v_mfma_f32_16x16x32_bf16 v[30:33], v[156:159], v[128:131], v[30:33]
	v_mfma_f32_16x16x32_bf16 v[34:37], v[144:147], v[132:135], v[34:37]
	v_mfma_f32_16x16x32_bf16 v[38:41], v[148:151], v[132:135], v[38:41]
	v_mfma_f32_16x16x32_bf16 v[42:45], v[152:155], v[132:135], v[42:45]
	v_mfma_f32_16x16x32_bf16 v[46:49], v[156:159], v[132:135], v[46:49]
	v_mfma_f32_16x16x32_bf16 v[50:53], v[144:147], v[140:143], v[50:53]
	v_mfma_f32_16x16x32_bf16 v[54:57], v[148:151], v[140:143], v[54:57]
	v_mfma_f32_16x16x32_bf16 v[58:61], v[152:155], v[140:143], v[58:61]
	v_mfma_f32_16x16x32_bf16 v[62:65], v[156:159], v[140:143], v[62:65]
	ds_read_b128 v[124:127], v86
	ds_read_b128 v[128:131], v86 offset:2048
	ds_read_b128 v[132:135], v86 offset:4096
	ds_read_b128 v[140:143], v86 offset:6144
	ds_read_b128 v[144:147], v87
	ds_read_b128 v[148:151], v87 offset:2048
	ds_read_b128 v[152:155], v87 offset:4096
	ds_read_b128 v[156:159], v87 offset:6144
	s_waitcnt lgkmcnt(8)
	s_nop 0
	s_waitcnt lgkmcnt(0)
	s_waitcnt vmcnt(0)
	s_barrier
	global_load_lds_dwordx4 v[80:81], off
	s_mov_b32 m0, s20
	v_mfma_f32_16x16x32_bf16 v[26:29], v[116:119], v[94:97], v[26:29]
	global_load_lds_dwordx4 v[78:79], off
	s_mov_b32 m0, s23
	v_mfma_f32_16x16x32_bf16 v[38:41], v[112:115], v[98:101], v[38:41]
	global_load_lds_dwordx4 v[76:77], off
	s_mov_b32 m0, s25
	v_mfma_f32_16x16x32_bf16 v[22:25], v[112:115], v[94:97], v[22:25]
	global_load_lds_dwordx4 v[74:75], off
	s_mov_b32 m0, s26
	v_mfma_f32_16x16x32_bf16 v[42:45], v[116:119], v[98:101], v[42:45]
	global_load_lds_dwordx4 v[72:73], off
	s_mov_b32 m0, s27
	v_mfma_f32_16x16x32_bf16 v[2:5], v[108:111], v[90:93], v[2:5]
	global_load_lds_dwordx4 v[70:71], off
	s_mov_b32 m0, s30
	v_mfma_f32_16x16x32_bf16 v[6:9], v[112:115], v[90:93], v[6:9]
	global_load_lds_dwordx4 v[68:69], off
	s_mov_b32 m0, s47
	v_mfma_f32_16x16x32_bf16 v[10:13], v[116:119], v[90:93], v[10:13]
	global_load_lds_dwordx4 v[66:67], off
	v_mfma_f32_16x16x32_bf16 v[14:17], v[120:123], v[90:93], v[14:17]
	v_mfma_f32_16x16x32_bf16 v[18:21], v[108:111], v[94:97], v[18:21]
	v_mfma_f32_16x16x32_bf16 v[30:33], v[120:123], v[94:97], v[30:33]
	v_mfma_f32_16x16x32_bf16 v[34:37], v[108:111], v[98:101], v[34:37]
	v_mfma_f32_16x16x32_bf16 v[46:49], v[120:123], v[98:101], v[46:49]
	v_mfma_f32_16x16x32_bf16 v[50:53], v[108:111], v[102:105], v[50:53]
	v_mfma_f32_16x16x32_bf16 v[54:57], v[112:115], v[102:105], v[54:57]
	v_mfma_f32_16x16x32_bf16 v[58:61], v[116:119], v[102:105], v[58:61]
	v_mfma_f32_16x16x32_bf16 v[62:65], v[120:123], v[102:105], v[62:65]
	ds_read_b128 v[66:69], v82
	ds_read_b128 v[70:73], v82 offset:2048
	ds_read_b128 v[74:77], v82 offset:4096
	ds_read_b128 v[78:81], v82 offset:6144
	ds_read_b128 v[90:93], v84
	ds_read_b128 v[94:97], v84 offset:2048
	ds_read_b128 v[98:101], v84 offset:4096
	ds_read_b128 v[102:105], v84 offset:6144
	v_mfma_f32_16x16x32_bf16 v[26:29], v[152:155], v[128:131], v[26:29]
	v_mfma_f32_16x16x32_bf16 v[38:41], v[148:151], v[132:135], v[38:41]
	v_mfma_f32_16x16x32_bf16 v[22:25], v[148:151], v[128:131], v[22:25]
	v_mfma_f32_16x16x32_bf16 v[42:45], v[152:155], v[132:135], v[42:45]
	v_mfma_f32_16x16x32_bf16 v[2:5], v[144:147], v[124:127], v[2:5]
	v_mfma_f32_16x16x32_bf16 v[6:9], v[148:151], v[124:127], v[6:9]
	v_mfma_f32_16x16x32_bf16 v[10:13], v[152:155], v[124:127], v[10:13]
	v_mfma_f32_16x16x32_bf16 v[14:17], v[156:159], v[124:127], v[14:17]
	v_mfma_f32_16x16x32_bf16 v[18:21], v[144:147], v[128:131], v[18:21]
	v_mfma_f32_16x16x32_bf16 v[30:33], v[156:159], v[128:131], v[30:33]
	v_mfma_f32_16x16x32_bf16 v[34:37], v[144:147], v[132:135], v[34:37]
	v_mfma_f32_16x16x32_bf16 v[46:49], v[156:159], v[132:135], v[46:49]
	v_mfma_f32_16x16x32_bf16 v[50:53], v[144:147], v[140:143], v[50:53]
	v_mfma_f32_16x16x32_bf16 v[54:57], v[148:151], v[140:143], v[54:57]
	v_mfma_f32_16x16x32_bf16 v[58:61], v[152:155], v[140:143], v[58:61]
	v_mfma_f32_16x16x32_bf16 v[62:65], v[156:159], v[140:143], v[62:65]
	ds_read_b128 v[108:111], v0
	ds_read_b128 v[112:115], v0 offset:2048
	ds_read_b128 v[116:119], v0 offset:4096
	ds_read_b128 v[120:123], v0 offset:6144
	ds_read_b128 v[124:127], v83
	ds_read_b128 v[128:131], v83 offset:2048
	ds_read_b128 v[132:135], v83 offset:4096
	ds_read_b128 v[140:143], v83 offset:6144
	s_waitcnt lgkmcnt(8)
	s_nop 0
	s_waitcnt lgkmcnt(0)
	v_mfma_f32_16x16x32_bf16 v[26:29], v[98:101], v[70:73], v[26:29]
	s_waitcnt vmcnt(0)
	s_barrier
; DI unsigned pk2(float a, float b) { f32x2 v = {a, b}; bfv2 r = __builtin_convertvector(v, bfv2); return __builtin_bit_cast(unsigned, r); }
; DI float bf_lo(unsigned u) { return __uint_as_float(u << 16); }
; DI float bf_hi(unsigned u) { return __uint_as_float(u & 0xffff0000u); }
; DI void gemm_dma(f32x4 (&acc)[4][4], const bf16_t* Ap, int lda, const bf16_t* Bp, int ldb, int K, char* lds) {
;     ...
; #pragma unroll
;     for (int mi = 0; mi < 4; ++mi)
; #pragma unroll
;       for (int ni = 0; ni < 4; ++ni) acc[mi][ni] = __builtin_amdgcn_mfma_f32_16x16x32_bf16(bfr[ni], af[mi], acc[mi][ni], 0, 0, 0);
;     asm volatile("s_waitcnt lgkmcnt(0)" : "+v"(ag[0]), "+v"(ag[1]), "+v"(ag[2]), "+v"(ag[3]), "+v"(bg[0]), "+v"(bg[1]), "+v"(bg[2]), "+v"(bg[3]) :: "memory");
; #pragma unroll
;     for (int mi = 0; mi < 4; ++mi)
; #pragma unroll
;       for (int ni = 0; ni < 4; ++ni) acc[mi][ni] = __builtin_amdgcn_mfma_f32_16x16x32_bf16(bg[ni], ag[mi], acc[mi][ni], 0, 0, 0);
;   }
; DI void phase_merge(const Params& p, int l, char* lds) {
;     ...
;     u32x2 pk[4][4];
; #pragma unroll
;     for (int mi = 0; mi < 4; ++mi) {
;       const int R = mt * 128 + wm * 64 + mi * 16 + l15;
; #pragma unroll
;       for (int ni = 0; ni < 4; ++ni) {
;         const int c = nt * 128 + wn * 64 + ni * 16 + quad * 4;
;         const u32x2 g1 = *(const u32x2*)(p.z + (size_t)R * NZ + C_MR + c);
;         const f32x4 v1 = a1[mi][ni];
;         pk[mi][ni][0] = pk2(bf_lo(g1[0]) * v1[0], bf_hi(g1[0]) * v1[1]);
;         pk[mi][ni][1] = pk2(bf_lo(g1[1]) * v1[2], bf_hi(g1[1]) * v1[3]);
;       }
;     }
	v_mfma_f32_16x16x32_bf16 v[38:41], v[94:97], v[74:77], v[38:41]
	v_mfma_f32_16x16x32_bf16 v[22:25], v[94:97], v[70:73], v[22:25]
	v_mfma_f32_16x16x32_bf16 v[42:45], v[98:101], v[74:77], v[42:45]
	v_mfma_f32_16x16x32_bf16 v[2:5], v[90:93], v[66:69], v[2:5]
	v_mfma_f32_16x16x32_bf16 v[6:9], v[94:97], v[66:69], v[6:9]
	v_mfma_f32_16x16x32_bf16 v[10:13], v[98:101], v[66:69], v[10:13]
	v_mfma_f32_16x16x32_bf16 v[14:17], v[102:105], v[66:69], v[14:17]
	v_mfma_f32_16x16x32_bf16 v[18:21], v[90:93], v[70:73], v[18:21]
	v_mfma_f32_16x16x32_bf16 v[30:33], v[102:105], v[70:73], v[30:33]
	v_mfma_f32_16x16x32_bf16 v[34:37], v[90:93], v[74:77], v[34:37]
	v_mfma_f32_16x16x32_bf16 v[46:49], v[102:105], v[74:77], v[46:49]
	v_mfma_f32_16x16x32_bf16 v[50:53], v[90:93], v[78:81], v[50:53]
	v_mfma_f32_16x16x32_bf16 v[54:57], v[94:97], v[78:81], v[54:57]
	v_mfma_f32_16x16x32_bf16 v[58:61], v[98:101], v[78:81], v[58:61]
	v_mfma_f32_16x16x32_bf16 v[62:65], v[102:105], v[78:81], v[62:65]
	ds_read_b128 v[66:69], v85
	ds_read_b128 v[70:73], v85 offset:2048
	ds_read_b128 v[74:77], v85 offset:4096
	ds_read_b128 v[78:81], v85 offset:6144
	ds_read_b128 v[90:93], v88
	ds_read_b128 v[94:97], v88 offset:2048
	ds_read_b128 v[98:101], v88 offset:4096
	ds_read_b128 v[102:105], v88 offset:6144
	v_lshl_add_u32 v88, s24, 7, v106
	v_ashrrev_i32_e32 v89, 31, v88
	v_mfma_f32_16x16x32_bf16 v[26:29], v[132:135], v[112:115], v[26:29]
	v_mfma_f32_16x16x32_bf16 v[38:41], v[128:131], v[116:119], v[38:41]
	v_mfma_f32_16x16x32_bf16 v[22:25], v[128:131], v[112:115], v[22:25]
	v_mfma_f32_16x16x32_bf16 v[42:45], v[132:135], v[116:119], v[42:45]
	v_mfma_f32_16x16x32_bf16 v[2:5], v[124:127], v[108:111], v[2:5]
	v_mfma_f32_16x16x32_bf16 v[6:9], v[128:131], v[108:111], v[6:9]
	v_mfma_f32_16x16x32_bf16 v[10:13], v[132:135], v[108:111], v[10:13]
	v_mfma_f32_16x16x32_bf16 v[14:17], v[140:143], v[108:111], v[14:17]
	v_mfma_f32_16x16x32_bf16 v[18:21], v[124:127], v[112:115], v[18:21]
	v_mfma_f32_16x16x32_bf16 v[30:33], v[140:143], v[112:115], v[30:33]
	v_mfma_f32_16x16x32_bf16 v[34:37], v[124:127], v[116:119], v[34:37]
	v_mfma_f32_16x16x32_bf16 v[46:49], v[140:143], v[116:119], v[46:49]
	v_mfma_f32_16x16x32_bf16 v[50:53], v[124:127], v[120:123], v[50:53]
	v_mfma_f32_16x16x32_bf16 v[54:57], v[128:131], v[120:123], v[54:57]
	v_mfma_f32_16x16x32_bf16 v[58:61], v[132:135], v[120:123], v[58:61]
	v_mfma_f32_16x16x32_bf16 v[62:65], v[140:143], v[120:123], v[62:65]
	ds_read_b128 v[82:85], v86
	ds_read_b128 v[108:111], v86 offset:2048
	ds_read_b128 v[112:115], v86 offset:4096
	ds_read_b128 v[116:119], v86 offset:6144
	ds_read_b128 v[120:123], v87
	ds_read_b128 v[124:127], v87 offset:2048
	ds_read_b128 v[128:131], v87 offset:4096
	ds_read_b128 v[132:135], v87 offset:6144
	s_waitcnt lgkmcnt(8)
	s_nop 0
	s_waitcnt lgkmcnt(0)
	v_mfma_f32_16x16x32_bf16 v[26:29], v[98:101], v[70:73], v[26:29]
	s_barrier
	v_mfma_f32_16x16x32_bf16 v[38:41], v[94:97], v[74:77], v[38:41]
	v_mfma_f32_16x16x32_bf16 v[22:25], v[94:97], v[70:73], v[22:25]
	v_mfma_f32_16x16x32_bf16 v[42:45], v[98:101], v[74:77], v[42:45]
	v_mfma_f32_16x16x32_bf16 v[10:13], v[98:101], v[66:69], v[10:13]
	v_mfma_f32_16x16x32_bf16 v[58:61], v[98:101], v[78:81], v[58:61]
	v_mfma_f32_16x16x32_bf16 v[98:101], v[128:131], v[108:111], v[26:29]
	v_mfma_f32_16x16x32_bf16 v[26:29], v[124:127], v[112:115], v[38:41]
	s_nop 2
	v_lshl_or_b32 v38, s22, 7, v107
	v_mov_b64_e32 v[40:41], s[10:11]
	v_ashrrev_i32_e32 v39, 31, v38
	v_mad_i64_i32 v[86:87], s[20:21], v88, s94, v[40:41]
	v_mfma_f32_16x16x32_bf16 v[6:9], v[94:97], v[66:69], v[6:9]
	v_mfma_f32_16x16x32_bf16 v[18:21], v[90:93], v[70:73], v[18:21]
	v_mfma_f32_16x16x32_bf16 v[30:33], v[102:105], v[70:73], v[30:33]
	v_lshlrev_b64 v[70:71], 1, v[38:39]
	v_mfma_f32_16x16x32_bf16 v[54:57], v[94:97], v[78:81], v[54:57]
	v_mfma_f32_16x16x32_bf16 v[94:97], v[124:127], v[108:111], v[22:25]
	v_mfma_f32_16x16x32_bf16 v[22:25], v[128:131], v[112:115], v[42:45]
	s_nop 2
	v_lshl_add_u64 v[42:43], v[86:87], 0, s[82:83]
	v_lshl_add_u64 v[44:45], v[42:43], 0, v[70:71]
	global_load_dwordx2 v[44:45], v[44:45], off
	v_mfma_f32_16x16x32_bf16 v[2:5], v[90:93], v[66:69], v[2:5]
	v_lshl_add_u64 v[86:87], v[86:87], 0, s[36:37]
	v_mfma_f32_16x16x32_bf16 v[46:49], v[102:105], v[74:77], v[46:49]
	v_mfma_f32_16x16x32_bf16 v[14:17], v[102:105], v[66:69], v[14:17]
	v_mfma_f32_16x16x32_bf16 v[66:69], v[120:123], v[82:85], v[2:5]
	v_mfma_f32_16x16x32_bf16 v[34:37], v[90:93], v[74:77], v[34:37]
	v_mfma_f32_16x16x32_bf16 v[50:53], v[90:93], v[78:81], v[50:53]
	v_mfma_f32_16x16x32_bf16 v[90:93], v[120:123], v[108:111], v[18:21]
	v_mfma_f32_16x16x32_bf16 v[18:21], v[132:135], v[112:115], v[46:49]
	v_mfma_f32_16x16x32_bf16 v[74:77], v[124:127], v[82:85], v[6:9]
	s_waitcnt vmcnt(0)
	s_nop 0
	v_lshlrev_b32_e32 v46, 16, v44
	v_and_b32_e32 v47, 0xffff0000, v44
	v_lshlrev_b32_e32 v44, 16, v45
	v_and_b32_e32 v45, 0xffff0000, v45
	v_pk_mul_f32 v[44:45], v[68:69], v[44:45]
	v_pk_mul_f32 v[46:47], v[66:67], v[46:47]
	v_cvt_pk_bf16_f32 v141, v44, v45
	v_or_b32_e32 v44, 16, v38
	v_ashrrev_i32_e32 v45, 31, v44
	v_lshlrev_b64 v[72:73], 1, v[44:45]
	v_lshl_add_u64 v[44:45], v[42:43], 0, v[72:73]
	global_load_dwordx2 v[44:45], v[44:45], off
	v_cvt_pk_bf16_f32 v142, v46, v47
	v_mfma_f32_16x16x32_bf16 v[62:65], v[102:105], v[78:81], v[62:65]
	s_waitcnt vmcnt(0)
; DI unsigned pk2(float a, float b) { f32x2 v = {a, b}; bfv2 r = __builtin_convertvector(v, bfv2); return __builtin_bit_cast(unsigned, r); }
; DI float bf_lo(unsigned u) { return __uint_as_float(u << 16); }
; DI float bf_hi(unsigned u) { return __uint_as_float(u & 0xffff0000u); }
; DI void phase_merge(const Params& p, int l, char* lds) {
;     ...
;     for (int mi = 0; mi < 4; ++mi) {
;       const int R = mt * 128 + wm * 64 + mi * 16 + l15;
; #pragma unroll
;       for (int ni = 0; ni < 4; ++ni) {
;         const int c = nt * 128 + wn * 64 + ni * 16 + quad * 4;
;         const u32x2 g1 = *(const u32x2*)(p.z + (size_t)R * NZ + C_MR + c);
;         const f32x4 v1 = a1[mi][ni];
;         pk[mi][ni][0] = pk2(bf_lo(g1[0]) * v1[0], bf_hi(g1[0]) * v1[1]);
;         pk[mi][ni][1] = pk2(bf_lo(g1[1]) * v1[2], bf_hi(g1[1]) * v1[3]);
;       }
;     }
	v_lshlrev_b32_e32 v46, 16, v44
	v_and_b32_e32 v47, 0xffff0000, v44
	v_lshlrev_b32_e32 v44, 16, v45
	v_and_b32_e32 v45, 0xffff0000, v45
	v_pk_mul_f32 v[44:45], v[76:77], v[44:45]
	v_mfma_f32_16x16x32_bf16 v[78:81], v[128:131], v[82:85], v[10:13]
	v_cvt_pk_bf16_f32 v139, v44, v45
	v_or_b32_e32 v44, 32, v38
	v_or_b32_e32 v38, 48, v38
	v_ashrrev_i32_e32 v45, 31, v44
	v_ashrrev_i32_e32 v39, 31, v38
	v_lshlrev_b64 v[68:69], 1, v[44:45]
	v_lshlrev_b64 v[66:67], 1, v[38:39]
	v_lshl_add_u64 v[44:45], v[42:43], 0, v[68:69]
	v_lshl_add_u64 v[38:39], v[42:43], 0, v[66:67]
	global_load_dwordx2 v[44:45], v[44:45], off
	v_mfma_f32_16x16x32_bf16 v[82:85], v[132:135], v[82:85], v[14:17]
	global_load_dwordx2 v[38:39], v[38:39], off
	v_pk_mul_f32 v[46:47], v[74:75], v[46:47]
	v_or_b32_e32 v76, 48, v88
	v_mfma_f32_16x16x32_bf16 v[30:33], v[132:135], v[108:111], v[30:33]
	v_cvt_pk_bf16_f32 v140, v46, v47
	v_mad_i64_i32 v[74:75], s[20:21], v76, s94, v[40:41]
	v_mfma_f32_16x16x32_bf16 v[2:5], v[132:135], v[116:119], v[62:65]
	v_ashrrev_i32_e32 v77, 31, v76
	s_waitcnt vmcnt(0)
	v_lshlrev_b32_e32 v46, 16, v44
	v_and_b32_e32 v47, 0xffff0000, v44
	v_lshlrev_b32_e32 v42, 16, v38
	v_and_b32_e32 v43, 0xffff0000, v38
	v_lshlrev_b32_e32 v38, 16, v39
	v_and_b32_e32 v39, 0xffff0000, v39
	v_pk_mul_f32 v[38:39], v[84:85], v[38:39]
	v_or_b32_e32 v84, 16, v88
	v_pk_mul_f32 v[42:43], v[82:83], v[42:43]
	v_mad_i64_i32 v[82:83], s[20:21], v84, s94, v[40:41]
	v_cvt_pk_bf16_f32 v132, v38, v39
	v_lshl_add_u64 v[38:39], v[82:83], 0, s[82:83]
	v_cvt_pk_bf16_f32 v133, v42, v43
	v_lshl_add_u64 v[42:43], v[38:39], 0, v[70:71]
	global_load_dwordx2 v[42:43], v[42:43], off
	v_lshlrev_b32_e32 v44, 16, v45
	v_and_b32_e32 v45, 0xffff0000, v45
	v_pk_mul_f32 v[44:45], v[80:81], v[44:45]
	v_mfma_f32_16x16x32_bf16 v[6:9], v[128:131], v[116:119], v[58:61]
	v_cvt_pk_bf16_f32 v134, v44, v45
	v_or_b32_e32 v80, 32, v88
	v_pk_mul_f32 v[46:47], v[78:79], v[46:47]
	v_mfma_f32_16x16x32_bf16 v[10:13], v[124:127], v[116:119], v[54:57]
	v_mad_i64_i32 v[78:79], s[20:21], v80, s94, v[40:41]
	v_lshl_add_u64 v[186:187], v[78:79], 0, s[82:83]
	v_lshl_add_u64 v[188:189], v[74:75], 0, s[82:83]
	v_lshl_add_u64 v[184:185], v[38:39], 0, v[72:73]
	global_load_dwordx2 v[162:163], v[184:185], off
	v_lshl_add_u64 v[190:191], v[38:39], 0, v[68:69]
	global_load_dwordx2 v[164:165], v[190:191], off
	v_lshl_add_u64 v[184:185], v[38:39], 0, v[66:67]
	global_load_dwordx2 v[166:167], v[184:185], off
	v_lshl_add_u64 v[190:191], v[186:187], 0, v[70:71]
	global_load_dwordx2 v[168:169], v[190:191], off
	v_lshl_add_u64 v[184:185], v[186:187], 0, v[72:73]
	global_load_dwordx2 v[170:171], v[184:185], off
	v_lshl_add_u64 v[190:191], v[186:187], 0, v[68:69]
	global_load_dwordx2 v[172:173], v[190:191], off
	v_lshl_add_u64 v[184:185], v[186:187], 0, v[66:67]
	global_load_dwordx2 v[174:175], v[184:185], off
	v_lshl_add_u64 v[190:191], v[188:189], 0, v[70:71]
	global_load_dwordx2 v[176:177], v[190:191], off
	v_lshl_add_u64 v[184:185], v[188:189], 0, v[72:73]
	global_load_dwordx2 v[178:179], v[184:185], off
	v_lshl_add_u64 v[190:191], v[188:189], 0, v[68:69]
	global_load_dwordx2 v[180:181], v[190:191], off
	v_lshl_add_u64 v[184:185], v[188:189], 0, v[66:67]
	global_load_dwordx2 v[182:183], v[184:185], off
	v_cvt_pk_bf16_f32 v135, v46, v47
	v_mfma_f32_16x16x32_bf16 v[34:37], v[120:123], v[112:115], v[34:37]
	v_lshlrev_b64 v[88:89], 11, v[88:89]
	v_ashrrev_i32_e32 v85, 31, v84
	v_ashrrev_i32_e32 v81, 31, v80
	v_mfma_f32_16x16x32_bf16 v[14:17], v[120:123], v[116:119], v[50:53]
	s_waitcnt vmcnt(11)
	v_lshlrev_b32_e32 v44, 16, v42
	v_and_b32_e32 v45, 0xffff0000, v42
	v_lshlrev_b32_e32 v42, 16, v43
	v_and_b32_e32 v43, 0xffff0000, v43
	v_pk_mul_f32 v[42:43], v[92:93], v[42:43]
	v_pk_mul_f32 v[44:45], v[90:91], v[44:45]
	v_cvt_pk_bf16_f32 v130, v42, v43
	v_cvt_pk_bf16_f32 v131, v44, v45
	s_waitcnt vmcnt(10)
	v_mov_b32_e32 v42, v162
	v_mov_b32_e32 v43, v163
	v_lshlrev_b32_e32 v44, 16, v42
	v_and_b32_e32 v45, 0xffff0000, v42
	v_lshlrev_b32_e32 v42, 16, v43
	v_and_b32_e32 v43, 0xffff0000, v43
	v_pk_mul_f32 v[42:43], v[96:97], v[42:43]
	v_pk_mul_f32 v[44:45], v[94:95], v[44:45]
	v_cvt_pk_bf16_f32 v128, v42, v43
	v_cvt_pk_bf16_f32 v129, v44, v45
	s_waitcnt vmcnt(8)
	v_mov_b32_e32 v42, v164
	v_mov_b32_e32 v43, v165
	v_mov_b32_e32 v38, v166
	v_mov_b32_e32 v39, v167
	v_lshlrev_b32_e32 v44, 16, v42
	v_and_b32_e32 v45, 0xffff0000, v42
	v_lshlrev_b32_e32 v42, 16, v43
	v_and_b32_e32 v43, 0xffff0000, v43
	v_pk_mul_f32 v[42:43], v[100:101], v[42:43]
	v_pk_mul_f32 v[44:45], v[98:99], v[44:45]
	v_cvt_pk_bf16_f32 v126, v42, v43
	v_lshlrev_b32_e32 v42, 16, v38
	v_and_b32_e32 v43, 0xffff0000, v38
	v_pk_mul_f32 v[30:31], v[30:31], v[42:43]
	v_cvt_pk_bf16_f32 v127, v44, v45
	v_cvt_pk_bf16_f32 v125, v30, v31
	v_lshlrev_b32_e32 v30, 16, v39
	v_and_b32_e32 v31, 0xffff0000, v39
	v_pk_mul_f32 v[30:31], v[32:33], v[30:31]
	s_nop 0
	v_cvt_pk_bf16_f32 v124, v30, v31
	v_lshl_add_u64 v[30:31], v[78:79], 0, s[82:83]
	s_waitcnt vmcnt(7)
	v_mov_b32_e32 v32, v168
	v_mov_b32_e32 v33, v169
	v_lshlrev_b32_e32 v38, 16, v32
	v_and_b32_e32 v39, 0xffff0000, v32
	v_lshlrev_b32_e32 v32, 16, v33
	v_and_b32_e32 v33, 0xffff0000, v33
	v_pk_mul_f32 v[32:33], v[36:37], v[32:33]
	v_pk_mul_f32 v[34:35], v[34:35], v[38:39]
	v_cvt_pk_bf16_f32 v122, v32, v33
	v_cvt_pk_bf16_f32 v123, v34, v35
	s_waitcnt vmcnt(6)
	v_mov_b32_e32 v32, v170
	v_mov_b32_e32 v33, v171
	v_lshlrev_b32_e32 v34, 16, v32
	v_and_b32_e32 v35, 0xffff0000, v32
	v_pk_mul_f32 v[26:27], v[26:27], v[34:35]
	s_nop 0
	v_cvt_pk_bf16_f32 v121, v26, v27
	v_lshlrev_b32_e32 v26, 16, v33
	v_and_b32_e32 v27, 0xffff0000, v33
	v_pk_mul_f32 v[26:27], v[28:29], v[26:27]
	s_nop 0
	v_cvt_pk_bf16_f32 v120, v26, v27
	s_waitcnt vmcnt(5)
; DI void gemm_dma(f32x4 (&acc)[4][4], const bf16_t* Ap, int lda, const bf16_t* Bp, int ldb, int K, char* lds) {
;     ...
;   const int lrow = lane >> 3, lpc = lane & 7;
;   const bf16_t* ga[4]; const bf16_t* gb[4];
; #pragma unroll
;   for (int i = 0; i < 4; ++i) {
;     const int row = (wave * 4 + i) * 8 + lrow; const int q = lpc ^ (row & 7);
;     ga[i] = Ap + (size_t)row * lda + q * 8; gb[i] = Bp + (size_t)row * ldb + q * 8;
;   }
;   auto issue = [&](int kt) {
;     char* sb = lds + (kt & 1) * 32768 + wave * 4096;
; #pragma unroll
;     for (int i = 0; i < 4; ++i) {
;       __builtin_amdgcn_global_load_lds((const unsigned*)(ga[i] + kt * 64), (LASP unsigned*)(sb + i * 1024), 16, 0, 0);
;       __builtin_amdgcn_global_load_lds((const unsigned*)(gb[i] + kt * 64), (LASP unsigned*)(sb + 16384 + i * 1024), 16, 0, 0);
;     }
;   };
;   const int sw = l15 & 7;
;   const unsigned lbase = (unsigned)(size_t)(LASP char*)lds;
;   const unsigned a0 = (unsigned)((wm * 64 + l15) * 128 + ((quad ^ sw) * 16)), a1 = (unsigned)((wm * 64 + l15) * 128 + (((4 + quad) ^ sw) * 16));
;   const unsigned b0 = 16384u + (unsigned)((wn * 64 + l15) * 128 + ((quad ^ sw) * 16)), b1 = 16384u + (unsigned)((wn * 64 + l15) * 128 + (((4 + quad) ^ sw) * 16));
;   asm volatile("s_waitcnt vmcnt(0)" ::: "memory");
;   __builtin_amdgcn_s_barrier();
;   asm volatile("" ::: "memory");
;   issue(0);
;   for (int kt = 0; kt < nk; ++kt) {
;     asm volatile("s_waitcnt vmcnt(0)" ::: "memory");
;     __builtin_amdgcn_s_barrier();
;     asm volatile("" ::: "memory");
;     if (kt + 1 < nk) issue(kt + 1);
;     const unsigned sa = lbase + (unsigned)((kt & 1) * 32768);
;     bf16x8 af[4], bfr[4], ag[4], bg[4];
;     asm volatile("ds_read_b128 %0, %8\n\tds_read_b128 %1, %8 offset:2048\n\tds_read_b128 %2, %8 offset:4096\n\tds_read_b128 %3, %8 offset:6144\n\t"
; DI void phase_merge(const Params& p, int l, char* lds) {
;     ...
;     for (int mi = 0; mi < 4; ++mi) {
;       const int R = mt * 128 + wm * 64 + mi * 16 + l15;
; #pragma unroll
;       for (int ni = 0; ni < 4; ++ni) {
;         const int c = nt * 128 + wn * 64 + ni * 16 + quad * 4;
;         const u32x2 g1 = *(const u32x2*)(p.z + (size_t)R * NZ + C_MR + c);
;         const f32x4 v1 = a1[mi][ni];
;         pk[mi][ni][0] = pk2(bf_lo(g1[0]) * v1[0], bf_hi(g1[0]) * v1[1]);
;         pk[mi][ni][1] = pk2(bf_lo(g1[1]) * v1[2], bf_hi(g1[1]) * v1[3]);
;       }
;     }
	v_mov_b32_e32 v26, v172
	v_mov_b32_e32 v27, v173
	v_lshlrev_b32_e32 v28, 16, v26
	v_and_b32_e32 v29, 0xffff0000, v26
	v_pk_mul_f32 v[22:23], v[22:23], v[28:29]
	s_nop 0
	v_cvt_pk_bf16_f32 v119, v22, v23
	v_lshlrev_b32_e32 v22, 16, v27
	v_and_b32_e32 v23, 0xffff0000, v27
	v_pk_mul_f32 v[22:23], v[24:25], v[22:23]
	s_nop 0
	v_cvt_pk_bf16_f32 v118, v22, v23
	s_waitcnt vmcnt(4)
	v_mov_b32_e32 v22, v174
	v_mov_b32_e32 v23, v175
	v_lshlrev_b32_e32 v24, 16, v22
	v_and_b32_e32 v25, 0xffff0000, v22
	v_pk_mul_f32 v[18:19], v[18:19], v[24:25]
	s_nop 0
	v_cvt_pk_bf16_f32 v117, v18, v19
	v_lshlrev_b32_e32 v18, 16, v23
	v_and_b32_e32 v19, 0xffff0000, v23
	v_pk_mul_f32 v[18:19], v[20:21], v[18:19]
	s_nop 0
	v_cvt_pk_bf16_f32 v116, v18, v19
	v_lshl_add_u64 v[18:19], v[74:75], 0, s[82:83]
	s_waitcnt vmcnt(3)
	v_mov_b32_e32 v20, v176
	v_mov_b32_e32 v21, v177
	v_lshlrev_b32_e32 v22, 16, v20
	v_and_b32_e32 v23, 0xffff0000, v20
	v_pk_mul_f32 v[14:15], v[14:15], v[22:23]
	s_nop 0
	v_cvt_pk_bf16_f32 v115, v14, v15
	v_lshlrev_b32_e32 v14, 16, v21
	v_and_b32_e32 v15, 0xffff0000, v21
	v_pk_mul_f32 v[14:15], v[16:17], v[14:15]
	s_nop 0
	v_cvt_pk_bf16_f32 v114, v14, v15
	s_waitcnt vmcnt(2)
	v_mov_b32_e32 v14, v178
	v_mov_b32_e32 v15, v179
	v_lshlrev_b32_e32 v16, 16, v14
	v_and_b32_e32 v17, 0xffff0000, v14
	v_pk_mul_f32 v[10:11], v[10:11], v[16:17]
	s_nop 0
	v_cvt_pk_bf16_f32 v113, v10, v11
	v_lshlrev_b32_e32 v10, 16, v15
	v_and_b32_e32 v11, 0xffff0000, v15
	v_pk_mul_f32 v[10:11], v[12:13], v[10:11]
	s_nop 0
	v_cvt_pk_bf16_f32 v112, v10, v11
	s_waitcnt vmcnt(1)
	v_mov_b32_e32 v10, v180
	v_mov_b32_e32 v11, v181
	v_lshlrev_b32_e32 v12, 16, v10
	v_and_b32_e32 v13, 0xffff0000, v10
	v_pk_mul_f32 v[6:7], v[6:7], v[12:13]
	v_mov_b32_e32 v10, v212
	v_cvt_pk_bf16_f32 v111, v6, v7
	v_lshlrev_b32_e32 v6, 16, v11
	v_and_b32_e32 v7, 0xffff0000, v11
	v_pk_mul_f32 v[6:7], v[8:9], v[6:7]
	s_nop 0
	v_cvt_pk_bf16_f32 v110, v6, v7
	s_waitcnt vmcnt(0)
	v_mov_b32_e32 v6, v182
	v_mov_b32_e32 v7, v183
	s_barrier
	v_readfirstlane_b32 s21, v10
	s_ashr_i32 s20, s21, 6
	v_bfe_u32 v0, v10, 3, 3
	s_lshl_b32 s25, s20, 12
	s_add_i32 s27, s25, 0x4000
	s_mov_b32 m0, s25
	s_or_b32 s41, s25, 0x400
	s_add_i32 s40, s25, 0x4400
	s_or_b32 s31, s25, 0x800
	s_add_i32 s30, s25, 0x4800
	s_or_b32 s26, s25, 0xc00
	v_bfe_u32 v11, v10, 4, 2
	v_and_b32_e32 v12, 7, v10
	s_add_i32 s24, s25, 0x4c00
	s_add_i32 s22, s25, 0x8c00
	s_add_i32 s23, s25, 0xcc00
	s_waitcnt vmcnt(0)
	v_lshlrev_b32_e32 v8, 16, v6
	v_and_b32_e32 v9, 0xffff0000, v6
	v_pk_mul_f32 v[2:3], v[2:3], v[8:9]
	s_nop 0
	v_cvt_pk_bf16_f32 v109, v2, v3
	v_lshlrev_b32_e32 v2, 16, v7
	v_and_b32_e32 v3, 0xffff0000, v7
	v_pk_mul_f32 v[2:3], v[4:5], v[2:3]
	s_nop 0
	v_cvt_pk_bf16_f32 v108, v2, v3
	v_lshl_or_b32 v2, s20, 5, v0
	v_bitop3_b32 v0, v0, v10, 7 bitop3:0x78
	v_lshlrev_b32_e32 v0, 4, v0
	v_ashrrev_i32_e32 v3, 31, v2
	v_lshl_add_u64 v[4:5], s[0:1], 0, v[0:1]
	v_lshl_add_u64 v[6:7], s[2:3], 0, v[0:1]
	v_lshlrev_b64 v[8:9], 10, v[2:3]
	v_lshl_add_u64 v[104:105], v[4:5], 0, v[8:9]
	v_lshl_add_u64 v[98:99], v[6:7], 0, v[8:9]
	v_or_b32_e32 v8, 8, v2
	v_ashrrev_i32_e32 v9, 31, v8
	v_lshlrev_b64 v[8:9], 10, v[8:9]
	v_lshl_add_u64 v[102:103], v[4:5], 0, v[8:9]
	v_lshl_add_u64 v[94:95], v[6:7], 0, v[8:9]
	v_or_b32_e32 v8, 16, v2
	global_load_lds_dwordx4 v[104:105], off
	s_mov_b32 m0, s27
	v_ashrrev_i32_e32 v9, 31, v8
	v_or_b32_e32 v2, 24, v2
	global_load_lds_dwordx4 v[98:99], off
	s_mov_b32 m0, s41
	v_lshlrev_b64 v[8:9], 10, v[8:9]
	v_ashrrev_i32_e32 v3, 31, v2
	global_load_lds_dwordx4 v[102:103], off
	s_mov_b32 m0, s40
	v_lshl_add_u64 v[100:101], v[4:5], 0, v[8:9]
	v_lshlrev_b64 v[2:3], 10, v[2:3]
	s_lshr_b32 s0, s21, 1
	global_load_lds_dwordx4 v[94:95], off
	s_mov_b32 m0, s31
	v_lshl_add_u64 v[92:93], v[6:7], 0, v[8:9]
	v_lshl_add_u64 v[96:97], v[4:5], 0, v[2:3]
	v_lshl_add_u64 v[90:91], v[6:7], 0, v[2:3]
	v_and_b32_e32 v2, 15, v10
	s_and_b32 s0, s0, 0x1ffffc0
	global_load_lds_dwordx4 v[100:101], off
	s_mov_b32 m0, s30
	v_or_b32_e32 v0, s0, v2
	global_load_lds_dwordx4 v[92:93], off
	s_mov_b32 m0, s26
	v_lshlrev_b32_e32 v3, 7, v0
	v_bitop3_b32 v0, v11, v10, 7 bitop3:0x78
	v_bitop3_b32 v5, v11, v12, 4 bitop3:0x36
	v_and_or_b32 v2, s21, 64, v2
	global_load_lds_dwordx4 v[96:97], off
	s_mov_b32 m0, s24
	v_lshlrev_b32_e32 v4, 4, v0
	v_lshlrev_b32_e32 v5, 4, v5
	v_lshlrev_b32_e32 v2, 7, v2
	global_load_lds_dwordx4 v[90:91], off
	s_add_i32 s1, s25, 0x8000
	v_or_b32_e32 v0, v3, v4
	v_or_b32_e32 v143, v3, v5
	v_or_b32_e32 v147, v2, v4
	v_or_b32_e32 v149, v2, v5
	s_waitcnt vmcnt(0)
	s_barrier
	s_add_i32 s0, s25, 0xc000
	v_lshl_add_u64 v[2:3], v[104:105], 0, s[28:29]
	s_mov_b32 m0, s1
	s_add_i32 s2, s25, 0x8400
	global_load_lds_dwordx4 v[2:3], off
	v_lshl_add_u64 v[2:3], v[98:99], 0, s[28:29]
	s_mov_b32 m0, s0
	s_add_i32 s3, s25, 0xc400
	global_load_lds_dwordx4 v[2:3], off
	v_lshl_add_u64 v[2:3], v[102:103], 0, s[28:29]
	s_mov_b32 m0, s2
	s_add_i32 s20, s25, 0x8800
	global_load_lds_dwordx4 v[2:3], off
	v_lshl_add_u64 v[2:3], v[94:95], 0, s[28:29]
	s_mov_b32 m0, s3
	s_add_i32 s21, s25, 0xc800
	global_load_lds_dwordx4 v[2:3], off
	v_lshl_add_u64 v[2:3], v[100:101], 0, s[28:29]
	s_mov_b32 m0, s20
	v_or_b32_e32 v144, 0x4000, v147
	global_load_lds_dwordx4 v[2:3], off
	v_lshl_add_u64 v[2:3], v[92:93], 0, s[28:29]
	s_mov_b32 m0, s21
	v_or_b32_e32 v145, 0x4000, v149
	global_load_lds_dwordx4 v[2:3], off
	v_lshl_add_u64 v[2:3], v[96:97], 0, s[28:29]
	s_mov_b32 m0, s22
	v_add_u32_e32 v146, 0x8000, v0
	global_load_lds_dwordx4 v[2:3], off
	v_lshl_add_u64 v[2:3], v[90:91], 0, s[28:29]
	s_mov_b32 m0, s23
	v_or_b32_e32 v147, 0xc000, v147
	global_load_lds_dwordx4 v[2:3], off
	ds_read_b128 v[2:5], v0
	ds_read_b128 v[6:9], v0 offset:2048
	ds_read_b128 v[10:13], v0 offset:4096
	ds_read_b128 v[14:17], v0 offset:6144
	ds_read_b128 v[18:21], v144
	ds_read_b128 v[22:25], v144 offset:2048
	ds_read_b128 v[26:29], v144 offset:4096
	ds_read_b128 v[30:33], v144 offset:6144
	s_mov_b32 m0, s25
	ds_read_b128 v[34:37], v143
	ds_read_b128 v[38:41], v143 offset:2048
	ds_read_b128 v[46:49], v143 offset:4096
	ds_read_b128 v[62:65], v143 offset:6144
	ds_read_b128 v[50:53], v145
	ds_read_b128 v[54:57], v145 offset:2048
	ds_read_b128 v[58:61], v145 offset:4096
	ds_read_b128 v[150:153], v145 offset:6144
	s_waitcnt lgkmcnt(8)
	v_add_u32_e32 v148, 0x8000, v143
	v_mfma_f32_16x16x32_bf16 v[42:45], v[18:21], v[2:5], 0
	s_waitcnt lgkmcnt(0)
	s_waitcnt vmcnt(0)
	s_barrier
; DI void gemm_dma(f32x4 (&acc)[4][4], const bf16_t* Ap, int lda, const bf16_t* Bp, int ldb, int K, char* lds) {
;     ...
;   for (int kt = 0; kt < nk; ++kt) {
;     asm volatile("s_waitcnt vmcnt(0)" ::: "memory");
;     __builtin_amdgcn_s_barrier();
;     asm volatile("" ::: "memory");
;     if (kt + 1 < nk) issue(kt + 1);
;     const unsigned sa = lbase + (unsigned)((kt & 1) * 32768);
;     bf16x8 af[4], bfr[4], ag[4], bg[4];
;     asm volatile("ds_read_b128 %0, %8\n\tds_read_b128 %1, %8 offset:2048\n\tds_read_b128 %2, %8 offset:4096\n\tds_read_b128 %3, %8 offset:6144\n\t"
;                  "ds_read_b128 %4, %9\n\tds_read_b128 %5, %9 offset:2048\n\tds_read_b128 %6, %9 offset:4096\n\tds_read_b128 %7, %9 offset:6144"
;                  : "=&v"(af[0]), "=&v"(af[1]), "=&v"(af[2]), "=&v"(af[3]), "=&v"(bfr[0]), "=&v"(bfr[1]), "=&v"(bfr[2]), "=&v"(bfr[3])
;                  : "v"(sa + a0), "v"(sa + b0) : "memory");
;     asm volatile("ds_read_b128 %0, %16\n\tds_read_b128 %1, %16 offset:2048\n\tds_read_b128 %2, %16 offset:4096\n\tds_read_b128 %3, %16 offset:6144\n\t"
;                  "ds_read_b128 %4, %17\n\tds_read_b128 %5, %17 offset:2048\n\tds_read_b128 %6, %17 offset:4096\n\tds_read_b128 %7, %17 offset:6144\n\t"
;                  "s_waitcnt lgkmcnt(8)"
;                  : "=&v"(ag[0]), "=&v"(ag[1]), "=&v"(ag[2]), "=&v"(ag[3]), "=&v"(bg[0]), "=&v"(bg[1]), "=&v"(bg[2]), "=&v"(bg[3]),
;                    "+v"(af[0]), "+v"(af[1]), "+v"(af[2]), "+v"(af[3]), "+v"(bfr[0]), "+v"(bfr[1]), "+v"(bfr[2]), "+v"(bfr[3])
;                  : "v"(sa + a1), "v"(sa + b1) : "memory");
; #pragma unroll
;     for (int mi = 0; mi < 4; ++mi)
; #pragma unroll
;       for (int ni = 0; ni < 4; ++ni) acc[mi][ni] = __builtin_amdgcn_mfma_f32_16x16x32_bf16(bfr[ni], af[mi], acc[mi][ni], 0, 0, 0);
;     asm volatile("s_waitcnt lgkmcnt(0)" : "+v"(ag[0]), "+v"(ag[1]), "+v"(ag[2]), "+v"(ag[3]), "+v"(bg[0]), "+v"(bg[1]), "+v"(bg[2]), "+v"(bg[3]) :: "memory");
; #pragma unroll
;     for (int mi = 0; mi < 4; ++mi)
; #pragma unroll
;       for (int ni = 0; ni < 4; ++ni) acc[mi][ni] = __builtin_amdgcn_mfma_f32_16x16x32_bf16(bg[ni], ag[mi], acc[mi][ni], 0, 0, 0);
	v_mfma_f32_16x16x32_bf16 v[154:157], v[22:25], v[2:5], 0
	v_or_b32_e32 v149, 0xc000, v149
	v_mfma_f32_16x16x32_bf16 v[162:165], v[26:29], v[2:5], 0
	v_mfma_f32_16x16x32_bf16 v[166:169], v[30:33], v[2:5], 0
	v_mfma_f32_16x16x32_bf16 v[170:173], v[18:21], v[6:9], 0
	v_mfma_f32_16x16x32_bf16 v[174:177], v[22:25], v[6:9], 0
	v_mfma_f32_16x16x32_bf16 v[178:181], v[26:29], v[6:9], 0
	v_mfma_f32_16x16x32_bf16 v[182:185], v[30:33], v[6:9], 0
	v_mfma_f32_16x16x32_bf16 v[186:189], v[18:21], v[10:13], 0
	v_mfma_f32_16x16x32_bf16 v[190:193], v[22:25], v[10:13], 0
	v_mfma_f32_16x16x32_bf16 v[194:197], v[26:29], v[10:13], 0
	v_mfma_f32_16x16x32_bf16 v[198:201], v[30:33], v[10:13], 0
	v_mfma_f32_16x16x32_bf16 v[202:205], v[18:21], v[14:17], 0
	v_mfma_f32_16x16x32_bf16 v[206:209], v[22:25], v[14:17], 0
	v_mfma_f32_16x16x32_bf16 v[232:235], v[26:29], v[14:17], 0
	v_mfma_f32_16x16x32_bf16 v[236:239], v[30:33], v[14:17], 0
	v_mfma_f32_16x16x32_bf16 v[2:5], v[50:53], v[34:37], v[42:45]
	v_mfma_f32_16x16x32_bf16 v[6:9], v[54:57], v[34:37], v[154:157]
	v_mfma_f32_16x16x32_bf16 v[10:13], v[58:61], v[34:37], v[162:165]
	v_mfma_f32_16x16x32_bf16 v[14:17], v[150:153], v[34:37], v[166:169]
	v_mfma_f32_16x16x32_bf16 v[18:21], v[50:53], v[38:41], v[170:173]
	v_mfma_f32_16x16x32_bf16 v[22:25], v[54:57], v[38:41], v[174:177]
	v_mfma_f32_16x16x32_bf16 v[26:29], v[58:61], v[38:41], v[178:181]
	v_mfma_f32_16x16x32_bf16 v[30:33], v[150:153], v[38:41], v[182:185]
	v_mfma_f32_16x16x32_bf16 v[34:37], v[50:53], v[46:49], v[186:189]
	v_mfma_f32_16x16x32_bf16 v[38:41], v[54:57], v[46:49], v[190:193]
	v_mfma_f32_16x16x32_bf16 v[42:45], v[58:61], v[46:49], v[194:197]
	v_mfma_f32_16x16x32_bf16 v[46:49], v[150:153], v[46:49], v[198:201]
	v_mfma_f32_16x16x32_bf16 v[50:53], v[50:53], v[62:65], v[202:205]
	v_mfma_f32_16x16x32_bf16 v[54:57], v[54:57], v[62:65], v[206:209]
	v_mfma_f32_16x16x32_bf16 v[58:61], v[58:61], v[62:65], v[232:235]
	v_mfma_f32_16x16x32_bf16 v[62:65], v[150:153], v[62:65], v[236:239]
	v_lshl_add_u64 v[150:151], v[104:105], 0, s[70:71]
	global_load_lds_dwordx4 v[150:151], off
	v_lshl_add_u64 v[150:151], v[98:99], 0, s[70:71]
	s_mov_b32 m0, s27
	s_nop 0
	global_load_lds_dwordx4 v[150:151], off
	v_lshl_add_u64 v[150:151], v[102:103], 0, s[70:71]
	s_mov_b32 m0, s41
	s_nop 0
	global_load_lds_dwordx4 v[150:151], off
	v_lshl_add_u64 v[150:151], v[94:95], 0, s[70:71]
	s_mov_b32 m0, s40
	s_nop 0
	global_load_lds_dwordx4 v[150:151], off
	v_lshl_add_u64 v[150:151], v[100:101], 0, s[70:71]
	s_mov_b32 m0, s31
	s_nop 0
	global_load_lds_dwordx4 v[150:151], off
	v_lshl_add_u64 v[150:151], v[92:93], 0, s[70:71]
	s_mov_b32 m0, s30
	s_nop 0
	global_load_lds_dwordx4 v[150:151], off
	v_lshl_add_u64 v[150:151], v[96:97], 0, s[70:71]
	s_mov_b32 m0, s26
	s_nop 0
	global_load_lds_dwordx4 v[150:151], off
	v_lshl_add_u64 v[150:151], v[90:91], 0, s[70:71]
	s_mov_b32 m0, s24
	s_nop 0
	global_load_lds_dwordx4 v[150:151], off
	ds_read_b128 v[150:153], v146
	ds_read_b128 v[154:157], v146 offset:2048
	ds_read_b128 v[162:165], v146 offset:4096
	ds_read_b128 v[166:169], v146 offset:6144
	ds_read_b128 v[170:173], v147
	ds_read_b128 v[174:177], v147 offset:2048
	ds_read_b128 v[178:181], v147 offset:4096
	ds_read_b128 v[182:185], v147 offset:6144
	s_mov_b32 m0, s1
	ds_read_b128 v[186:189], v148
	ds_read_b128 v[190:193], v148 offset:2048
	ds_read_b128 v[194:197], v148 offset:4096
	ds_read_b128 v[198:201], v148 offset:6144
	ds_read_b128 v[202:205], v149
	ds_read_b128 v[206:209], v149 offset:2048
	ds_read_b128 v[232:235], v149 offset:4096
	ds_read_b128 v[236:239], v149 offset:6144
	s_waitcnt lgkmcnt(8)
	s_nop 0
	s_waitcnt lgkmcnt(0)
	v_mfma_f32_16x16x32_bf16 v[2:5], v[170:173], v[150:153], v[2:5]
	s_waitcnt vmcnt(0)
	s_barrier
	v_mfma_f32_16x16x32_bf16 v[6:9], v[174:177], v[150:153], v[6:9]
	v_mfma_f32_16x16x32_bf16 v[10:13], v[178:181], v[150:153], v[10:13]
	v_mfma_f32_16x16x32_bf16 v[14:17], v[182:185], v[150:153], v[14:17]
	v_lshl_add_u64 v[150:151], v[104:105], 0, s[72:73]
	global_load_lds_dwordx4 v[150:151], off
	v_lshl_add_u64 v[150:151], v[98:99], 0, s[72:73]
	s_mov_b32 m0, s0
	v_mfma_f32_16x16x32_bf16 v[18:21], v[170:173], v[154:157], v[18:21]
	global_load_lds_dwordx4 v[150:151], off
	v_lshl_add_u64 v[150:151], v[102:103], 0, s[72:73]
	s_mov_b32 m0, s2
	v_mfma_f32_16x16x32_bf16 v[22:25], v[174:177], v[154:157], v[22:25]
	global_load_lds_dwordx4 v[150:151], off
	v_lshl_add_u64 v[150:151], v[94:95], 0, s[72:73]
	s_mov_b32 m0, s3
	v_mfma_f32_16x16x32_bf16 v[26:29], v[178:181], v[154:157], v[26:29]
	global_load_lds_dwordx4 v[150:151], off
	v_lshl_add_u64 v[150:151], v[100:101], 0, s[72:73]
	s_mov_b32 m0, s20
	v_mfma_f32_16x16x32_bf16 v[30:33], v[182:185], v[154:157], v[30:33]
	global_load_lds_dwordx4 v[150:151], off
	v_lshl_add_u64 v[150:151], v[92:93], 0, s[72:73]
	s_mov_b32 m0, s21
	v_mfma_f32_16x16x32_bf16 v[34:37], v[170:173], v[162:165], v[34:37]
	global_load_lds_dwordx4 v[150:151], off
	v_lshl_add_u64 v[150:151], v[96:97], 0, s[72:73]
	v_mfma_f32_16x16x32_bf16 v[38:41], v[174:177], v[162:165], v[38:41]
	s_mov_b32 m0, s22
	s_nop 0
	global_load_lds_dwordx4 v[150:151], off
	v_mfma_f32_16x16x32_bf16 v[42:45], v[178:181], v[162:165], v[42:45]
	v_lshl_add_u64 v[150:151], v[90:91], 0, s[72:73]
	s_mov_b32 m0, s23
	v_mfma_f32_16x16x32_bf16 v[46:49], v[182:185], v[162:165], v[46:49]
	global_load_lds_dwordx4 v[150:151], off
	s_mov_b32 m0, s25
	v_mfma_f32_16x16x32_bf16 v[50:53], v[170:173], v[166:169], v[50:53]
	v_mfma_f32_16x16x32_bf16 v[54:57], v[174:177], v[166:169], v[54:57]
	v_mfma_f32_16x16x32_bf16 v[58:61], v[178:181], v[166:169], v[58:61]
	v_mfma_f32_16x16x32_bf16 v[62:65], v[182:185], v[166:169], v[62:65]
; DI void gemm_dma(f32x4 (&acc)[4][4], const bf16_t* Ap, int lda, const bf16_t* Bp, int ldb, int K, char* lds) {
;     ...
;   for (int kt = 0; kt < nk; ++kt) {
;     asm volatile("s_waitcnt vmcnt(0)" ::: "memory");
;     __builtin_amdgcn_s_barrier();
;     asm volatile("" ::: "memory");
;     if (kt + 1 < nk) issue(kt + 1);
;     const unsigned sa = lbase + (unsigned)((kt & 1) * 32768);
;     bf16x8 af[4], bfr[4], ag[4], bg[4];
;     asm volatile("ds_read_b128 %0, %8\n\tds_read_b128 %1, %8 offset:2048\n\tds_read_b128 %2, %8 offset:4096\n\tds_read_b128 %3, %8 offset:6144\n\t"
;                  "ds_read_b128 %4, %9\n\tds_read_b128 %5, %9 offset:2048\n\tds_read_b128 %6, %9 offset:4096\n\tds_read_b128 %7, %9 offset:6144"
;                  : "=&v"(af[0]), "=&v"(af[1]), "=&v"(af[2]), "=&v"(af[3]), "=&v"(bfr[0]), "=&v"(bfr[1]), "=&v"(bfr[2]), "=&v"(bfr[3])
;                  : "v"(sa + a0), "v"(sa + b0) : "memory");
;     asm volatile("ds_read_b128 %0, %16\n\tds_read_b128 %1, %16 offset:2048\n\tds_read_b128 %2, %16 offset:4096\n\tds_read_b128 %3, %16 offset:6144\n\t"
;                  "ds_read_b128 %4, %17\n\tds_read_b128 %5, %17 offset:2048\n\tds_read_b128 %6, %17 offset:4096\n\tds_read_b128 %7, %17 offset:6144\n\t"
;                  "s_waitcnt lgkmcnt(8)"
;                  : "=&v"(ag[0]), "=&v"(ag[1]), "=&v"(ag[2]), "=&v"(ag[3]), "=&v"(bg[0]), "=&v"(bg[1]), "=&v"(bg[2]), "=&v"(bg[3]),
;                    "+v"(af[0]), "+v"(af[1]), "+v"(af[2]), "+v"(af[3]), "+v"(bfr[0]), "+v"(bfr[1]), "+v"(bfr[2]), "+v"(bfr[3])
;                  : "v"(sa + a1), "v"(sa + b1) : "memory");
; #pragma unroll
;     for (int mi = 0; mi < 4; ++mi)
; #pragma unroll
;       for (int ni = 0; ni < 4; ++ni) acc[mi][ni] = __builtin_amdgcn_mfma_f32_16x16x32_bf16(bfr[ni], af[mi], acc[mi][ni], 0, 0, 0);
;     asm volatile("s_waitcnt lgkmcnt(0)" : "+v"(ag[0]), "+v"(ag[1]), "+v"(ag[2]), "+v"(ag[3]), "+v"(bg[0]), "+v"(bg[1]), "+v"(bg[2]), "+v"(bg[3]) :: "memory");
; #pragma unroll
;     for (int mi = 0; mi < 4; ++mi)
; #pragma unroll
;       for (int ni = 0; ni < 4; ++ni) acc[mi][ni] = __builtin_amdgcn_mfma_f32_16x16x32_bf16(bg[ni], ag[mi], acc[mi][ni], 0, 0, 0);
	ds_read_b128 v[150:153], v0
	ds_read_b128 v[154:157], v0 offset:2048
	ds_read_b128 v[162:165], v0 offset:4096
	ds_read_b128 v[166:169], v0 offset:6144
	ds_read_b128 v[170:173], v144
	ds_read_b128 v[174:177], v144 offset:2048
	ds_read_b128 v[178:181], v144 offset:4096
	ds_read_b128 v[182:185], v144 offset:6144
	v_mfma_f32_16x16x32_bf16 v[2:5], v[202:205], v[186:189], v[2:5]
	v_mfma_f32_16x16x32_bf16 v[6:9], v[206:209], v[186:189], v[6:9]
	v_mfma_f32_16x16x32_bf16 v[10:13], v[232:235], v[186:189], v[10:13]
	v_mfma_f32_16x16x32_bf16 v[14:17], v[236:239], v[186:189], v[14:17]
	v_mfma_f32_16x16x32_bf16 v[18:21], v[202:205], v[190:193], v[18:21]
	v_mfma_f32_16x16x32_bf16 v[22:25], v[206:209], v[190:193], v[22:25]
	v_mfma_f32_16x16x32_bf16 v[26:29], v[232:235], v[190:193], v[26:29]
	v_mfma_f32_16x16x32_bf16 v[30:33], v[236:239], v[190:193], v[30:33]
	v_mfma_f32_16x16x32_bf16 v[34:37], v[202:205], v[194:197], v[34:37]
	v_mfma_f32_16x16x32_bf16 v[38:41], v[206:209], v[194:197], v[38:41]
	v_mfma_f32_16x16x32_bf16 v[42:45], v[232:235], v[194:197], v[42:45]
	v_mfma_f32_16x16x32_bf16 v[46:49], v[236:239], v[194:197], v[46:49]
	v_mfma_f32_16x16x32_bf16 v[50:53], v[202:205], v[198:201], v[50:53]
	v_mfma_f32_16x16x32_bf16 v[54:57], v[206:209], v[198:201], v[54:57]
	v_mfma_f32_16x16x32_bf16 v[58:61], v[232:235], v[198:201], v[58:61]
	v_mfma_f32_16x16x32_bf16 v[62:65], v[236:239], v[198:201], v[62:65]
	ds_read_b128 v[186:189], v143
	ds_read_b128 v[190:193], v143 offset:2048
	ds_read_b128 v[194:197], v143 offset:4096
	ds_read_b128 v[198:201], v143 offset:6144
	ds_read_b128 v[202:205], v145
	ds_read_b128 v[206:209], v145 offset:2048
	ds_read_b128 v[232:235], v145 offset:4096
	ds_read_b128 v[236:239], v145 offset:6144
	s_waitcnt lgkmcnt(8)
	s_nop 0
	s_waitcnt lgkmcnt(0)
	v_mfma_f32_16x16x32_bf16 v[2:5], v[170:173], v[150:153], v[2:5]
	s_waitcnt vmcnt(0)
	s_barrier
	v_mfma_f32_16x16x32_bf16 v[6:9], v[174:177], v[150:153], v[6:9]
	v_mfma_f32_16x16x32_bf16 v[10:13], v[178:181], v[150:153], v[10:13]
	v_mfma_f32_16x16x32_bf16 v[14:17], v[182:185], v[150:153], v[14:17]
	v_lshl_add_u64 v[150:151], v[104:105], 0, s[68:69]
	global_load_lds_dwordx4 v[150:151], off
	v_lshl_add_u64 v[150:151], v[98:99], 0, s[68:69]
	s_mov_b32 m0, s27
	v_mfma_f32_16x16x32_bf16 v[18:21], v[170:173], v[154:157], v[18:21]
	global_load_lds_dwordx4 v[150:151], off
	v_lshl_add_u64 v[150:151], v[102:103], 0, s[68:69]
	s_mov_b32 m0, s41
	v_mfma_f32_16x16x32_bf16 v[22:25], v[174:177], v[154:157], v[22:25]
	global_load_lds_dwordx4 v[150:151], off
	v_lshl_add_u64 v[150:151], v[94:95], 0, s[68:69]
	s_mov_b32 m0, s40
	v_mfma_f32_16x16x32_bf16 v[26:29], v[178:181], v[154:157], v[26:29]
	global_load_lds_dwordx4 v[150:151], off
	v_lshl_add_u64 v[150:151], v[100:101], 0, s[68:69]
	s_mov_b32 m0, s31
	v_mfma_f32_16x16x32_bf16 v[30:33], v[182:185], v[154:157], v[30:33]
	global_load_lds_dwordx4 v[150:151], off
	v_lshl_add_u64 v[150:151], v[92:93], 0, s[68:69]
	s_mov_b32 m0, s30
	v_mfma_f32_16x16x32_bf16 v[34:37], v[170:173], v[162:165], v[34:37]
	global_load_lds_dwordx4 v[150:151], off
	v_lshl_add_u64 v[150:151], v[96:97], 0, s[68:69]
	v_mfma_f32_16x16x32_bf16 v[38:41], v[174:177], v[162:165], v[38:41]
	s_mov_b32 m0, s26
	s_nop 0
	global_load_lds_dwordx4 v[150:151], off
	v_mfma_f32_16x16x32_bf16 v[42:45], v[178:181], v[162:165], v[42:45]
	v_lshl_add_u64 v[150:151], v[90:91], 0, s[68:69]
	s_mov_b32 m0, s24
	v_mfma_f32_16x16x32_bf16 v[46:49], v[182:185], v[162:165], v[46:49]
	global_load_lds_dwordx4 v[150:151], off
	s_mov_b32 m0, s1
	v_mfma_f32_16x16x32_bf16 v[50:53], v[170:173], v[166:169], v[50:53]
	v_mfma_f32_16x16x32_bf16 v[54:57], v[174:177], v[166:169], v[54:57]
	v_mfma_f32_16x16x32_bf16 v[58:61], v[178:181], v[166:169], v[58:61]
	v_mfma_f32_16x16x32_bf16 v[62:65], v[182:185], v[166:169], v[62:65]
	ds_read_b128 v[150:153], v146
	ds_read_b128 v[154:157], v146 offset:2048
	ds_read_b128 v[162:165], v146 offset:4096
	ds_read_b128 v[166:169], v146 offset:6144
	ds_read_b128 v[170:173], v147
	ds_read_b128 v[174:177], v147 offset:2048
	ds_read_b128 v[178:181], v147 offset:4096
	ds_read_b128 v[182:185], v147 offset:6144
	v_mfma_f32_16x16x32_bf16 v[2:5], v[202:205], v[186:189], v[2:5]
	v_mfma_f32_16x16x32_bf16 v[6:9], v[206:209], v[186:189], v[6:9]
	v_mfma_f32_16x16x32_bf16 v[10:13], v[232:235], v[186:189], v[10:13]
	v_mfma_f32_16x16x32_bf16 v[14:17], v[236:239], v[186:189], v[14:17]
	v_mfma_f32_16x16x32_bf16 v[18:21], v[202:205], v[190:193], v[18:21]
	v_mfma_f32_16x16x32_bf16 v[22:25], v[206:209], v[190:193], v[22:25]
	v_mfma_f32_16x16x32_bf16 v[26:29], v[232:235], v[190:193], v[26:29]
	v_mfma_f32_16x16x32_bf16 v[30:33], v[236:239], v[190:193], v[30:33]
	v_mfma_f32_16x16x32_bf16 v[34:37], v[202:205], v[194:197], v[34:37]
	v_mfma_f32_16x16x32_bf16 v[38:41], v[206:209], v[194:197], v[38:41]
	v_mfma_f32_16x16x32_bf16 v[42:45], v[232:235], v[194:197], v[42:45]
	v_mfma_f32_16x16x32_bf16 v[46:49], v[236:239], v[194:197], v[46:49]
	v_mfma_f32_16x16x32_bf16 v[50:53], v[202:205], v[198:201], v[50:53]
	v_mfma_f32_16x16x32_bf16 v[54:57], v[206:209], v[198:201], v[54:57]
	v_mfma_f32_16x16x32_bf16 v[58:61], v[232:235], v[198:201], v[58:61]
	v_mfma_f32_16x16x32_bf16 v[62:65], v[236:239], v[198:201], v[62:65]
	ds_read_b128 v[186:189], v148
	ds_read_b128 v[190:193], v148 offset:2048
	ds_read_b128 v[194:197], v148 offset:4096
	ds_read_b128 v[198:201], v148 offset:6144
	ds_read_b128 v[202:205], v149
	ds_read_b128 v[206:209], v149 offset:2048
	ds_read_b128 v[232:235], v149 offset:4096
	ds_read_b128 v[236:239], v149 offset:6144
	s_waitcnt lgkmcnt(8)
	s_nop 0
	s_waitcnt lgkmcnt(0)
	v_mfma_f32_16x16x32_bf16 v[2:5], v[170:173], v[150:153], v[2:5]
	s_waitcnt vmcnt(0)
	s_barrier
; DI void gemm_dma(f32x4 (&acc)[4][4], const bf16_t* Ap, int lda, const bf16_t* Bp, int ldb, int K, char* lds) {
;     ...
;   for (int kt = 0; kt < nk; ++kt) {
;     asm volatile("s_waitcnt vmcnt(0)" ::: "memory");
;     __builtin_amdgcn_s_barrier();
;     asm volatile("" ::: "memory");
;     if (kt + 1 < nk) issue(kt + 1);
;     const unsigned sa = lbase + (unsigned)((kt & 1) * 32768);
;     bf16x8 af[4], bfr[4], ag[4], bg[4];
;     asm volatile("ds_read_b128 %0, %8\n\tds_read_b128 %1, %8 offset:2048\n\tds_read_b128 %2, %8 offset:4096\n\tds_read_b128 %3, %8 offset:6144\n\t"
;                  "ds_read_b128 %4, %9\n\tds_read_b128 %5, %9 offset:2048\n\tds_read_b128 %6, %9 offset:4096\n\tds_read_b128 %7, %9 offset:6144"
;                  : "=&v"(af[0]), "=&v"(af[1]), "=&v"(af[2]), "=&v"(af[3]), "=&v"(bfr[0]), "=&v"(bfr[1]), "=&v"(bfr[2]), "=&v"(bfr[3])
;                  : "v"(sa + a0), "v"(sa + b0) : "memory");
;     asm volatile("ds_read_b128 %0, %16\n\tds_read_b128 %1, %16 offset:2048\n\tds_read_b128 %2, %16 offset:4096\n\tds_read_b128 %3, %16 offset:6144\n\t"
;                  "ds_read_b128 %4, %17\n\tds_read_b128 %5, %17 offset:2048\n\tds_read_b128 %6, %17 offset:4096\n\tds_read_b128 %7, %17 offset:6144\n\t"
;                  "s_waitcnt lgkmcnt(8)"
;                  : "=&v"(ag[0]), "=&v"(ag[1]), "=&v"(ag[2]), "=&v"(ag[3]), "=&v"(bg[0]), "=&v"(bg[1]), "=&v"(bg[2]), "=&v"(bg[3]),
;                    "+v"(af[0]), "+v"(af[1]), "+v"(af[2]), "+v"(af[3]), "+v"(bfr[0]), "+v"(bfr[1]), "+v"(bfr[2]), "+v"(bfr[3])
;                  : "v"(sa + a1), "v"(sa + b1) : "memory");
; #pragma unroll
;     for (int mi = 0; mi < 4; ++mi)
; #pragma unroll
;       for (int ni = 0; ni < 4; ++ni) acc[mi][ni] = __builtin_amdgcn_mfma_f32_16x16x32_bf16(bfr[ni], af[mi], acc[mi][ni], 0, 0, 0);
;     asm volatile("s_waitcnt lgkmcnt(0)" : "+v"(ag[0]), "+v"(ag[1]), "+v"(ag[2]), "+v"(ag[3]), "+v"(bg[0]), "+v"(bg[1]), "+v"(bg[2]), "+v"(bg[3]) :: "memory");
; #pragma unroll
;     for (int mi = 0; mi < 4; ++mi)
; #pragma unroll
;       for (int ni = 0; ni < 4; ++ni) acc[mi][ni] = __builtin_amdgcn_mfma_f32_16x16x32_bf16(bg[ni], ag[mi], acc[mi][ni], 0, 0, 0);
	v_mfma_f32_16x16x32_bf16 v[6:9], v[174:177], v[150:153], v[6:9]
	v_mfma_f32_16x16x32_bf16 v[10:13], v[178:181], v[150:153], v[10:13]
	v_mfma_f32_16x16x32_bf16 v[14:17], v[182:185], v[150:153], v[14:17]
	v_lshl_add_u64 v[150:151], v[104:105], 0, s[78:79]
	global_load_lds_dwordx4 v[150:151], off
	v_lshl_add_u64 v[150:151], v[98:99], 0, s[78:79]
	s_mov_b32 m0, s0
	v_mfma_f32_16x16x32_bf16 v[18:21], v[170:173], v[154:157], v[18:21]
	global_load_lds_dwordx4 v[150:151], off
	v_lshl_add_u64 v[150:151], v[102:103], 0, s[78:79]
	s_mov_b32 m0, s2
	v_mfma_f32_16x16x32_bf16 v[22:25], v[174:177], v[154:157], v[22:25]
	global_load_lds_dwordx4 v[150:151], off
	v_lshl_add_u64 v[150:151], v[94:95], 0, s[78:79]
	s_mov_b32 m0, s3
	v_mfma_f32_16x16x32_bf16 v[26:29], v[178:181], v[154:157], v[26:29]
	global_load_lds_dwordx4 v[150:151], off
	v_lshl_add_u64 v[150:151], v[100:101], 0, s[78:79]
	s_mov_b32 m0, s20
	v_mfma_f32_16x16x32_bf16 v[30:33], v[182:185], v[154:157], v[30:33]
	global_load_lds_dwordx4 v[150:151], off
	v_lshl_add_u64 v[150:151], v[92:93], 0, s[78:79]
	s_mov_b32 m0, s21
	v_mfma_f32_16x16x32_bf16 v[34:37], v[170:173], v[162:165], v[34:37]
	global_load_lds_dwordx4 v[150:151], off
	v_lshl_add_u64 v[150:151], v[96:97], 0, s[78:79]
	v_mfma_f32_16x16x32_bf16 v[38:41], v[174:177], v[162:165], v[38:41]
	s_mov_b32 m0, s22
	s_nop 0
	global_load_lds_dwordx4 v[150:151], off
	v_mfma_f32_16x16x32_bf16 v[42:45], v[178:181], v[162:165], v[42:45]
	v_lshl_add_u64 v[150:151], v[90:91], 0, s[78:79]
	s_mov_b32 m0, s23
	v_mfma_f32_16x16x32_bf16 v[46:49], v[182:185], v[162:165], v[46:49]
	global_load_lds_dwordx4 v[150:151], off
	s_mov_b32 m0, s25
	v_mfma_f32_16x16x32_bf16 v[50:53], v[170:173], v[166:169], v[50:53]
	v_mfma_f32_16x16x32_bf16 v[54:57], v[174:177], v[166:169], v[54:57]
	v_mfma_f32_16x16x32_bf16 v[58:61], v[178:181], v[166:169], v[58:61]
	v_mfma_f32_16x16x32_bf16 v[62:65], v[182:185], v[166:169], v[62:65]
	ds_read_b128 v[150:153], v0
	ds_read_b128 v[154:157], v0 offset:2048
	ds_read_b128 v[162:165], v0 offset:4096
	ds_read_b128 v[166:169], v0 offset:6144
	ds_read_b128 v[170:173], v144
	ds_read_b128 v[174:177], v144 offset:2048
	ds_read_b128 v[178:181], v144 offset:4096
	ds_read_b128 v[182:185], v144 offset:6144
	v_mfma_f32_16x16x32_bf16 v[2:5], v[202:205], v[186:189], v[2:5]
	v_mfma_f32_16x16x32_bf16 v[6:9], v[206:209], v[186:189], v[6:9]
	v_mfma_f32_16x16x32_bf16 v[10:13], v[232:235], v[186:189], v[10:13]
	v_mfma_f32_16x16x32_bf16 v[14:17], v[236:239], v[186:189], v[14:17]
	v_mfma_f32_16x16x32_bf16 v[18:21], v[202:205], v[190:193], v[18:21]
	v_mfma_f32_16x16x32_bf16 v[22:25], v[206:209], v[190:193], v[22:25]
	v_mfma_f32_16x16x32_bf16 v[26:29], v[232:235], v[190:193], v[26:29]
	v_mfma_f32_16x16x32_bf16 v[30:33], v[236:239], v[190:193], v[30:33]
	v_mfma_f32_16x16x32_bf16 v[34:37], v[202:205], v[194:197], v[34:37]
	v_mfma_f32_16x16x32_bf16 v[38:41], v[206:209], v[194:197], v[38:41]
	v_mfma_f32_16x16x32_bf16 v[42:45], v[232:235], v[194:197], v[42:45]
	v_mfma_f32_16x16x32_bf16 v[46:49], v[236:239], v[194:197], v[46:49]
	v_mfma_f32_16x16x32_bf16 v[50:53], v[202:205], v[198:201], v[50:53]
	v_mfma_f32_16x16x32_bf16 v[54:57], v[206:209], v[198:201], v[54:57]
	v_mfma_f32_16x16x32_bf16 v[58:61], v[232:235], v[198:201], v[58:61]
	v_mfma_f32_16x16x32_bf16 v[62:65], v[236:239], v[198:201], v[62:65]
	ds_read_b128 v[186:189], v143
	ds_read_b128 v[190:193], v143 offset:2048
	ds_read_b128 v[194:197], v143 offset:4096
	ds_read_b128 v[198:201], v143 offset:6144
	ds_read_b128 v[202:205], v145
	ds_read_b128 v[206:209], v145 offset:2048
	ds_read_b128 v[232:235], v145 offset:4096
	ds_read_b128 v[236:239], v145 offset:6144
	s_waitcnt lgkmcnt(8)
	s_nop 0
	s_waitcnt lgkmcnt(0)
	v_mfma_f32_16x16x32_bf16 v[2:5], v[170:173], v[150:153], v[2:5]
	s_waitcnt vmcnt(0)
	s_barrier
	v_mfma_f32_16x16x32_bf16 v[6:9], v[174:177], v[150:153], v[6:9]
	v_mfma_f32_16x16x32_bf16 v[10:13], v[178:181], v[150:153], v[10:13]
	v_mfma_f32_16x16x32_bf16 v[14:17], v[182:185], v[150:153], v[14:17]
	v_lshl_add_u64 v[150:151], v[104:105], 0, s[80:81]
	global_load_lds_dwordx4 v[150:151], off
	v_lshl_add_u64 v[150:151], v[98:99], 0, s[80:81]
	s_mov_b32 m0, s27
	v_mfma_f32_16x16x32_bf16 v[18:21], v[170:173], v[154:157], v[18:21]
	global_load_lds_dwordx4 v[150:151], off
	v_lshl_add_u64 v[150:151], v[102:103], 0, s[80:81]
	s_mov_b32 m0, s41
	v_mfma_f32_16x16x32_bf16 v[22:25], v[174:177], v[154:157], v[22:25]
	global_load_lds_dwordx4 v[150:151], off
	v_lshl_add_u64 v[150:151], v[94:95], 0, s[80:81]
	s_mov_b32 m0, s40
	v_mfma_f32_16x16x32_bf16 v[26:29], v[178:181], v[154:157], v[26:29]
	global_load_lds_dwordx4 v[150:151], off
	v_lshl_add_u64 v[150:151], v[100:101], 0, s[80:81]
	s_mov_b32 m0, s31
	v_mfma_f32_16x16x32_bf16 v[30:33], v[182:185], v[154:157], v[30:33]
	global_load_lds_dwordx4 v[150:151], off
	v_lshl_add_u64 v[150:151], v[92:93], 0, s[80:81]
	s_mov_b32 m0, s30
	v_mfma_f32_16x16x32_bf16 v[34:37], v[170:173], v[162:165], v[34:37]
	global_load_lds_dwordx4 v[150:151], off
	v_lshl_add_u64 v[150:151], v[96:97], 0, s[80:81]
	v_mfma_f32_16x16x32_bf16 v[38:41], v[174:177], v[162:165], v[38:41]
	s_mov_b32 m0, s26
	v_lshl_add_u64 v[104:105], v[104:105], 0, s[88:89]
	global_load_lds_dwordx4 v[150:151], off
	v_mfma_f32_16x16x32_bf16 v[42:45], v[178:181], v[162:165], v[42:45]
	v_lshl_add_u64 v[150:151], v[90:91], 0, s[80:81]
	s_mov_b32 m0, s24
	v_lshl_add_u64 v[98:99], v[98:99], 0, s[88:89]
	v_mfma_f32_16x16x32_bf16 v[46:49], v[182:185], v[162:165], v[46:49]
	global_load_lds_dwordx4 v[150:151], off
	s_mov_b32 m0, s1
	v_mfma_f32_16x16x32_bf16 v[50:53], v[170:173], v[166:169], v[50:53]
	v_lshl_add_u64 v[94:95], v[94:95], 0, s[88:89]
; DI void gemm_dma(f32x4 (&acc)[4][4], const bf16_t* Ap, int lda, const bf16_t* Bp, int ldb, int K, char* lds) {
;     ...
;   for (int kt = 0; kt < nk; ++kt) {
;     asm volatile("s_waitcnt vmcnt(0)" ::: "memory");
;     __builtin_amdgcn_s_barrier();
;     asm volatile("" ::: "memory");
;     if (kt + 1 < nk) issue(kt + 1);
;     const unsigned sa = lbase + (unsigned)((kt & 1) * 32768);
;     bf16x8 af[4], bfr[4], ag[4], bg[4];
;     asm volatile("ds_read_b128 %0, %8\n\tds_read_b128 %1, %8 offset:2048\n\tds_read_b128 %2, %8 offset:4096\n\tds_read_b128 %3, %8 offset:6144\n\t"
;                  "ds_read_b128 %4, %9\n\tds_read_b128 %5, %9 offset:2048\n\tds_read_b128 %6, %9 offset:4096\n\tds_read_b128 %7, %9 offset:6144"
;                  : "=&v"(af[0]), "=&v"(af[1]), "=&v"(af[2]), "=&v"(af[3]), "=&v"(bfr[0]), "=&v"(bfr[1]), "=&v"(bfr[2]), "=&v"(bfr[3])
;                  : "v"(sa + a0), "v"(sa + b0) : "memory");
;     asm volatile("ds_read_b128 %0, %16\n\tds_read_b128 %1, %16 offset:2048\n\tds_read_b128 %2, %16 offset:4096\n\tds_read_b128 %3, %16 offset:6144\n\t"
;                  "ds_read_b128 %4, %17\n\tds_read_b128 %5, %17 offset:2048\n\tds_read_b128 %6, %17 offset:4096\n\tds_read_b128 %7, %17 offset:6144\n\t"
;                  "s_waitcnt lgkmcnt(8)"
;                  : "=&v"(ag[0]), "=&v"(ag[1]), "=&v"(ag[2]), "=&v"(ag[3]), "=&v"(bg[0]), "=&v"(bg[1]), "=&v"(bg[2]), "=&v"(bg[3]),
;                    "+v"(af[0]), "+v"(af[1]), "+v"(af[2]), "+v"(af[3]), "+v"(bfr[0]), "+v"(bfr[1]), "+v"(bfr[2]), "+v"(bfr[3])
;                  : "v"(sa + a1), "v"(sa + b1) : "memory");
; #pragma unroll
;     for (int mi = 0; mi < 4; ++mi)
; #pragma unroll
;       for (int ni = 0; ni < 4; ++ni) acc[mi][ni] = __builtin_amdgcn_mfma_f32_16x16x32_bf16(bfr[ni], af[mi], acc[mi][ni], 0, 0, 0);
;     asm volatile("s_waitcnt lgkmcnt(0)" : "+v"(ag[0]), "+v"(ag[1]), "+v"(ag[2]), "+v"(ag[3]), "+v"(bg[0]), "+v"(bg[1]), "+v"(bg[2]), "+v"(bg[3]) :: "memory");
; #pragma unroll
;     for (int mi = 0; mi < 4; ++mi)
; #pragma unroll
;       for (int ni = 0; ni < 4; ++ni) acc[mi][ni] = __builtin_amdgcn_mfma_f32_16x16x32_bf16(bg[ni], ag[mi], acc[mi][ni], 0, 0, 0);
	v_lshl_add_u64 v[92:93], v[92:93], 0, s[88:89]
	v_lshl_add_u64 v[90:91], v[90:91], 0, s[88:89]
	v_mfma_f32_16x16x32_bf16 v[54:57], v[174:177], v[166:169], v[54:57]
	v_mfma_f32_16x16x32_bf16 v[58:61], v[178:181], v[166:169], v[58:61]
	v_mfma_f32_16x16x32_bf16 v[62:65], v[182:185], v[166:169], v[62:65]
	ds_read_b128 v[150:153], v146
	ds_read_b128 v[154:157], v146 offset:2048
	ds_read_b128 v[162:165], v146 offset:4096
	ds_read_b128 v[166:169], v146 offset:6144
	ds_read_b128 v[170:173], v147
	ds_read_b128 v[174:177], v147 offset:2048
	ds_read_b128 v[178:181], v147 offset:4096
	ds_read_b128 v[182:185], v147 offset:6144
	v_mfma_f32_16x16x32_bf16 v[2:5], v[202:205], v[186:189], v[2:5]
	v_mfma_f32_16x16x32_bf16 v[6:9], v[206:209], v[186:189], v[6:9]
	v_mfma_f32_16x16x32_bf16 v[10:13], v[232:235], v[186:189], v[10:13]
	v_mfma_f32_16x16x32_bf16 v[14:17], v[236:239], v[186:189], v[14:17]
	v_mfma_f32_16x16x32_bf16 v[18:21], v[202:205], v[190:193], v[18:21]
	v_mfma_f32_16x16x32_bf16 v[22:25], v[206:209], v[190:193], v[22:25]
	v_mfma_f32_16x16x32_bf16 v[26:29], v[232:235], v[190:193], v[26:29]
	v_mfma_f32_16x16x32_bf16 v[30:33], v[236:239], v[190:193], v[30:33]
	v_mfma_f32_16x16x32_bf16 v[34:37], v[202:205], v[194:197], v[34:37]
	v_mfma_f32_16x16x32_bf16 v[38:41], v[206:209], v[194:197], v[38:41]
	v_mfma_f32_16x16x32_bf16 v[42:45], v[232:235], v[194:197], v[42:45]
	v_mfma_f32_16x16x32_bf16 v[46:49], v[236:239], v[194:197], v[46:49]
	v_mfma_f32_16x16x32_bf16 v[50:53], v[202:205], v[198:201], v[50:53]
	v_mfma_f32_16x16x32_bf16 v[54:57], v[206:209], v[198:201], v[54:57]
	v_mfma_f32_16x16x32_bf16 v[58:61], v[232:235], v[198:201], v[58:61]
	v_mfma_f32_16x16x32_bf16 v[62:65], v[236:239], v[198:201], v[62:65]
	ds_read_b128 v[186:189], v148
	ds_read_b128 v[190:193], v148 offset:2048
	ds_read_b128 v[194:197], v148 offset:4096
	ds_read_b128 v[198:201], v148 offset:6144
	ds_read_b128 v[202:205], v149
	ds_read_b128 v[206:209], v149 offset:2048
	ds_read_b128 v[232:235], v149 offset:4096
	ds_read_b128 v[236:239], v149 offset:6144
	s_waitcnt lgkmcnt(8)
	s_nop 0
	s_waitcnt lgkmcnt(0)
	s_waitcnt vmcnt(0)
	s_barrier
	global_load_lds_dwordx4 v[104:105], off
	s_mov_b32 m0, s0
	v_mfma_f32_16x16x32_bf16 v[2:5], v[170:173], v[150:153], v[2:5]
	global_load_lds_dwordx4 v[98:99], off
	v_lshl_add_u64 v[98:99], v[102:103], 0, s[88:89]
	v_mfma_f32_16x16x32_bf16 v[6:9], v[174:177], v[150:153], v[6:9]
	s_mov_b32 m0, s2
	s_mul_i32 s0, s38, s49
	global_load_lds_dwordx4 v[98:99], off
	v_mfma_f32_16x16x32_bf16 v[10:13], v[178:181], v[150:153], v[10:13]
	s_mov_b32 m0, s3
	s_add_i32 s0, s0, s87
	global_load_lds_dwordx4 v[94:95], off
	v_mfma_f32_16x16x32_bf16 v[14:17], v[182:185], v[150:153], v[14:17]
	v_lshl_add_u64 v[94:95], v[100:101], 0, s[88:89]
	s_mov_b32 m0, s20
	s_cmp_ge_u32 s39, s48
	v_mfma_f32_16x16x32_bf16 v[30:33], v[182:185], v[154:157], v[30:33]
	global_load_lds_dwordx4 v[94:95], off
	s_mov_b32 m0, s21
	v_mfma_f32_16x16x32_bf16 v[34:37], v[170:173], v[162:165], v[34:37]
	global_load_lds_dwordx4 v[92:93], off
	v_lshl_add_u64 v[92:93], v[96:97], 0, s[88:89]
	v_mfma_f32_16x16x32_bf16 v[18:21], v[170:173], v[154:157], v[18:21]
	s_mov_b32 m0, s22
	s_nop 0
	global_load_lds_dwordx4 v[92:93], off
	v_mfma_f32_16x16x32_bf16 v[22:25], v[174:177], v[154:157], v[22:25]
	s_mov_b32 m0, s23
	s_nop 0
	global_load_lds_dwordx4 v[90:91], off
	v_mfma_f32_16x16x32_bf16 v[26:29], v[178:181], v[154:157], v[26:29]
	v_mfma_f32_16x16x32_bf16 v[38:41], v[174:177], v[162:165], v[38:41]
	v_mfma_f32_16x16x32_bf16 v[42:45], v[178:181], v[162:165], v[42:45]
	v_mfma_f32_16x16x32_bf16 v[46:49], v[182:185], v[162:165], v[46:49]
	v_mfma_f32_16x16x32_bf16 v[50:53], v[170:173], v[166:169], v[50:53]
	v_mfma_f32_16x16x32_bf16 v[54:57], v[174:177], v[166:169], v[54:57]
	v_mfma_f32_16x16x32_bf16 v[58:61], v[178:181], v[166:169], v[58:61]
	v_mfma_f32_16x16x32_bf16 v[62:65], v[182:185], v[166:169], v[62:65]
	ds_read_b128 v[90:93], v0
	ds_read_b128 v[94:97], v0 offset:2048
	ds_read_b128 v[98:101], v0 offset:4096
	ds_read_b128 v[102:105], v0 offset:6144
	ds_read_b128 v[150:153], v144
	ds_read_b128 v[154:157], v144 offset:2048
	ds_read_b128 v[162:165], v144 offset:4096
	ds_read_b128 v[166:169], v144 offset:6144
	v_mfma_f32_16x16x32_bf16 v[2:5], v[202:205], v[186:189], v[2:5]
	v_mfma_f32_16x16x32_bf16 v[6:9], v[206:209], v[186:189], v[6:9]
	v_mfma_f32_16x16x32_bf16 v[10:13], v[232:235], v[186:189], v[10:13]
	v_mfma_f32_16x16x32_bf16 v[14:17], v[236:239], v[186:189], v[14:17]
	v_mfma_f32_16x16x32_bf16 v[30:33], v[236:239], v[190:193], v[30:33]
	v_mfma_f32_16x16x32_bf16 v[34:37], v[202:205], v[194:197], v[34:37]
	v_mfma_f32_16x16x32_bf16 v[18:21], v[202:205], v[190:193], v[18:21]
	v_mfma_f32_16x16x32_bf16 v[22:25], v[206:209], v[190:193], v[22:25]
	v_mfma_f32_16x16x32_bf16 v[26:29], v[232:235], v[190:193], v[26:29]
	v_mfma_f32_16x16x32_bf16 v[38:41], v[206:209], v[194:197], v[38:41]
	v_mfma_f32_16x16x32_bf16 v[42:45], v[232:235], v[194:197], v[42:45]
	v_mfma_f32_16x16x32_bf16 v[46:49], v[236:239], v[194:197], v[46:49]
	v_mfma_f32_16x16x32_bf16 v[50:53], v[202:205], v[198:201], v[50:53]
	v_mfma_f32_16x16x32_bf16 v[54:57], v[206:209], v[198:201], v[54:57]
	v_mfma_f32_16x16x32_bf16 v[58:61], v[232:235], v[198:201], v[58:61]
	v_mfma_f32_16x16x32_bf16 v[62:65], v[236:239], v[198:201], v[62:65]
	ds_read_b128 v[170:173], v143
	ds_read_b128 v[174:177], v143 offset:2048
	ds_read_b128 v[178:181], v143 offset:4096
	ds_read_b128 v[182:185], v143 offset:6144
	ds_read_b128 v[186:189], v145
	ds_read_b128 v[190:193], v145 offset:2048
	ds_read_b128 v[194:197], v145 offset:4096
	ds_read_b128 v[198:201], v145 offset:6144
	s_waitcnt lgkmcnt(8)
	s_nop 0
	s_waitcnt lgkmcnt(0)
	v_mfma_f32_16x16x32_bf16 v[2:5], v[150:153], v[90:93], v[2:5]
	s_waitcnt vmcnt(0)
	s_barrier
; DI unsigned pk2(float a, float b) { f32x2 v = {a, b}; bfv2 r = __builtin_convertvector(v, bfv2); return __builtin_bit_cast(unsigned, r); }
; DI float bf_lo(unsigned u) { return __uint_as_float(u << 16); }
; DI float bf_hi(unsigned u) { return __uint_as_float(u & 0xffff0000u); }
; DI void gemm_dma(f32x4 (&acc)[4][4], const bf16_t* Ap, int lda, const bf16_t* Bp, int ldb, int K, char* lds) {
;     ...
;     for (int mi = 0; mi < 4; ++mi)
; #pragma unroll
;       for (int ni = 0; ni < 4; ++ni) acc[mi][ni] = __builtin_amdgcn_mfma_f32_16x16x32_bf16(bfr[ni], af[mi], acc[mi][ni], 0, 0, 0);
;     asm volatile("s_waitcnt lgkmcnt(0)" : "+v"(ag[0]), "+v"(ag[1]), "+v"(ag[2]), "+v"(ag[3]), "+v"(bg[0]), "+v"(bg[1]), "+v"(bg[2]), "+v"(bg[3]) :: "memory");
; #pragma unroll
;     for (int mi = 0; mi < 4; ++mi)
; #pragma unroll
;       for (int ni = 0; ni < 4; ++ni) acc[mi][ni] = __builtin_amdgcn_mfma_f32_16x16x32_bf16(bg[ni], ag[mi], acc[mi][ni], 0, 0, 0);
; DI void phase_merge(const Params& p, int l, char* lds) {
;     ...
; #pragma unroll
;     for (int mi = 0; mi < 4; ++mi) {
;       const int R = mt * 128 + wm * 64 + mi * 16 + l15;
; #pragma unroll
;       for (int ni = 0; ni < 4; ++ni) {
;         const int c = nt * 128 + wn * 64 + ni * 16 + quad * 4;
;         const u32x2 g2 = *(const u32x2*)(p.z + (size_t)R * NZ + C_MA + c);
;         const f32x4 v2 = a1[mi][ni]; const u32x2 u1 = pk[mi][ni];
;         u32x2 o;
;         o[0] = pk2(bf_lo(u1[0]) + bf_lo(g2[0]) * v2[0], bf_hi(u1[0]) + bf_hi(g2[0]) * v2[1]);
;         o[1] = pk2(bf_lo(u1[1]) + bf_lo(g2[1]) * v2[2], bf_hi(u1[1]) + bf_hi(g2[1]) * v2[3]);
;         *(u32x2*)(p.hn + (size_t)R * DM + c) = o;
;       }
	v_mfma_f32_16x16x32_bf16 v[6:9], v[154:157], v[90:93], v[6:9]
	v_mfma_f32_16x16x32_bf16 v[10:13], v[162:165], v[90:93], v[10:13]
	v_mfma_f32_16x16x32_bf16 v[14:17], v[166:169], v[90:93], v[14:17]
	v_mfma_f32_16x16x32_bf16 v[30:33], v[166:169], v[94:97], v[30:33]
	v_mfma_f32_16x16x32_bf16 v[34:37], v[150:153], v[98:101], v[34:37]
	v_mfma_f32_16x16x32_bf16 v[18:21], v[150:153], v[94:97], v[18:21]
	v_mfma_f32_16x16x32_bf16 v[22:25], v[154:157], v[94:97], v[22:25]
	v_mfma_f32_16x16x32_bf16 v[26:29], v[162:165], v[94:97], v[26:29]
	v_mfma_f32_16x16x32_bf16 v[38:41], v[154:157], v[98:101], v[38:41]
	v_mfma_f32_16x16x32_bf16 v[42:45], v[162:165], v[98:101], v[42:45]
	v_mfma_f32_16x16x32_bf16 v[46:49], v[166:169], v[98:101], v[46:49]
	v_mfma_f32_16x16x32_bf16 v[50:53], v[150:153], v[102:105], v[50:53]
	v_mfma_f32_16x16x32_bf16 v[54:57], v[154:157], v[102:105], v[54:57]
	v_mfma_f32_16x16x32_bf16 v[58:61], v[162:165], v[102:105], v[58:61]
	v_mfma_f32_16x16x32_bf16 v[62:65], v[166:169], v[102:105], v[62:65]
	ds_read_b128 v[90:93], v146
	ds_read_b128 v[94:97], v146 offset:2048
	ds_read_b128 v[98:101], v146 offset:4096
	ds_read_b128 v[102:105], v146 offset:6144
	ds_read_b128 v[150:153], v147
	ds_read_b128 v[154:157], v147 offset:2048
	ds_read_b128 v[162:165], v147 offset:4096
	ds_read_b128 v[166:169], v147 offset:6144
	v_mfma_f32_16x16x32_bf16 v[2:5], v[186:189], v[170:173], v[2:5]
	v_mfma_f32_16x16x32_bf16 v[6:9], v[190:193], v[170:173], v[6:9]
	v_mfma_f32_16x16x32_bf16 v[10:13], v[194:197], v[170:173], v[10:13]
	v_mfma_f32_16x16x32_bf16 v[14:17], v[198:201], v[170:173], v[14:17]
	v_mfma_f32_16x16x32_bf16 v[30:33], v[198:201], v[174:177], v[30:33]
	v_mfma_f32_16x16x32_bf16 v[34:37], v[186:189], v[178:181], v[34:37]
	v_mfma_f32_16x16x32_bf16 v[18:21], v[186:189], v[174:177], v[18:21]
	v_mfma_f32_16x16x32_bf16 v[22:25], v[190:193], v[174:177], v[22:25]
	v_mfma_f32_16x16x32_bf16 v[26:29], v[194:197], v[174:177], v[26:29]
	v_mfma_f32_16x16x32_bf16 v[38:41], v[190:193], v[178:181], v[38:41]
	v_mfma_f32_16x16x32_bf16 v[42:45], v[194:197], v[178:181], v[42:45]
	v_mfma_f32_16x16x32_bf16 v[46:49], v[198:201], v[178:181], v[46:49]
	v_mfma_f32_16x16x32_bf16 v[50:53], v[186:189], v[182:185], v[50:53]
	v_mfma_f32_16x16x32_bf16 v[54:57], v[190:193], v[182:185], v[54:57]
	v_mfma_f32_16x16x32_bf16 v[58:61], v[194:197], v[182:185], v[58:61]
	v_mfma_f32_16x16x32_bf16 v[62:65], v[198:201], v[182:185], v[62:65]
	ds_read_b128 v[144:147], v148
	ds_read_b128 v[170:173], v148 offset:2048
	ds_read_b128 v[174:177], v148 offset:4096
	ds_read_b128 v[178:181], v148 offset:6144
	ds_read_b128 v[182:185], v149
	ds_read_b128 v[186:189], v149 offset:2048
	ds_read_b128 v[190:193], v149 offset:4096
	ds_read_b128 v[194:197], v149 offset:6144
	s_waitcnt lgkmcnt(8)
	s_nop 0
	s_waitcnt lgkmcnt(0)
	v_mfma_f32_16x16x32_bf16 v[2:5], v[150:153], v[90:93], v[2:5]
	s_barrier
	v_mfma_f32_16x16x32_bf16 v[6:9], v[154:157], v[90:93], v[6:9]
	v_mfma_f32_16x16x32_bf16 v[10:13], v[162:165], v[90:93], v[10:13]
	v_mfma_f32_16x16x32_bf16 v[14:17], v[166:169], v[90:93], v[14:17]
	v_mfma_f32_16x16x32_bf16 v[30:33], v[166:169], v[94:97], v[30:33]
	v_mfma_f32_16x16x32_bf16 v[90:93], v[150:153], v[98:101], v[34:37]
	v_mfma_f32_16x16x32_bf16 v[34:37], v[194:197], v[170:173], v[30:33]
	v_mfma_f32_16x16x32_bf16 v[30:33], v[182:185], v[174:177], v[90:93]
	s_nop 5
	v_lshl_add_u64 v[90:91], v[86:87], 0, v[70:71]
	global_load_dwordx2 v[90:91], v[90:91], off
	v_mfma_f32_16x16x32_bf16 v[18:21], v[150:153], v[94:97], v[18:21]
	v_lshlrev_b32_e32 v92, 16, v142
	v_and_b32_e32 v93, 0xffff0000, v142
	v_mfma_f32_16x16x32_bf16 v[22:25], v[154:157], v[94:97], v[22:25]
	v_mfma_f32_16x16x32_bf16 v[26:29], v[162:165], v[94:97], v[26:29]
	v_mfma_f32_16x16x32_bf16 v[94:97], v[154:157], v[98:101], v[38:41]
	v_mfma_f32_16x16x32_bf16 v[148:151], v[150:153], v[102:105], v[50:53]
	v_mfma_f32_16x16x32_bf16 v[152:155], v[154:157], v[102:105], v[54:57]
	v_mfma_f32_16x16x32_bf16 v[156:159], v[162:165], v[102:105], v[58:61]
	v_mfma_f32_16x16x32_bf16 v[102:105], v[166:169], v[102:105], v[62:65]
	v_mfma_f32_16x16x32_bf16 v[62:65], v[182:185], v[144:147], v[2:5]
	v_mfma_f32_16x16x32_bf16 v[38:41], v[190:193], v[170:173], v[26:29]
	v_mfma_f32_16x16x32_bf16 v[26:29], v[186:189], v[174:177], v[94:97]
	v_mfma_f32_16x16x32_bf16 v[58:61], v[186:189], v[144:147], v[6:9]
	s_waitcnt vmcnt(0)
	s_nop 0
	v_lshlrev_b32_e32 v94, 16, v90
	v_and_b32_e32 v95, 0xffff0000, v90
	s_nop 0
	v_pk_fma_f32 v[62:63], v[62:63], v[94:95], v[92:93]
	v_lshlrev_b32_e32 v92, 16, v91
	v_cvt_pk_bf16_f32 v90, v62, v63
	v_lshlrev_b32_e32 v62, 16, v141
	v_and_b32_e32 v63, 0xffff0000, v141
	v_and_b32_e32 v93, 0xffff0000, v91
	v_pk_fma_f32 v[62:63], v[64:65], v[92:93], v[62:63]
	v_lshl_add_u64 v[64:65], v[86:87], 0, v[72:73]
	v_cvt_pk_bf16_f32 v91, v62, v63
	v_lshl_add_u64 v[62:63], s[8:9], 0, v[88:89]
	v_lshl_add_u64 v[62:63], v[62:63], 0, v[70:71]
	global_store_dwordx2 v[62:63], v[90:91], off
	global_load_dwordx2 v[64:65], v[64:65], off
	v_lshlrev_b32_e32 v88, 16, v140
	v_and_b32_e32 v89, 0xffff0000, v140
	v_mfma_f32_16x16x32_bf16 v[54:57], v[190:193], v[144:147], v[10:13]
	s_waitcnt vmcnt(0)
	v_lshlrev_b32_e32 v90, 16, v64
	v_and_b32_e32 v91, 0xffff0000, v64
	v_pk_fma_f32 v[58:59], v[58:59], v[90:91], v[88:89]
	v_lshlrev_b32_e32 v88, 16, v139
	v_and_b32_e32 v89, 0xffff0000, v139
	v_lshlrev_b32_e32 v64, 16, v65
	v_and_b32_e32 v65, 0xffff0000, v65
	v_pk_fma_f32 v[60:61], v[60:61], v[64:65], v[88:89]
	v_cvt_pk_bf16_f32 v58, v58, v59
	v_cvt_pk_bf16_f32 v59, v60, v61
	global_store_dwordx2 v[62:63], v[58:59], off offset:32
	v_lshl_add_u64 v[58:59], v[86:87], 0, v[68:69]
	global_load_dwordx2 v[58:59], v[58:59], off
	v_lshlrev_b32_e32 v60, 16, v135
	v_and_b32_e32 v61, 0xffff0000, v135
	v_mfma_f32_16x16x32_bf16 v[50:53], v[194:197], v[144:147], v[14:17]
	s_waitcnt vmcnt(0)
; DI unsigned pk2(float a, float b) { f32x2 v = {a, b}; bfv2 r = __builtin_convertvector(v, bfv2); return __builtin_bit_cast(unsigned, r); }
; DI float bf_lo(unsigned u) { return __uint_as_float(u << 16); }
; DI float bf_hi(unsigned u) { return __uint_as_float(u & 0xffff0000u); }
; DI void phase_merge(const Params& p, int l, char* lds) {
;     ...
; #pragma unroll
;     for (int mi = 0; mi < 4; ++mi) {
;       const int R = mt * 128 + wm * 64 + mi * 16 + l15;
; #pragma unroll
;       for (int ni = 0; ni < 4; ++ni) {
;         const int c = nt * 128 + wn * 64 + ni * 16 + quad * 4;
;         const u32x2 g2 = *(const u32x2*)(p.z + (size_t)R * NZ + C_MA + c);
;         const f32x4 v2 = a1[mi][ni]; const u32x2 u1 = pk[mi][ni];
;         u32x2 o;
;         o[0] = pk2(bf_lo(u1[0]) + bf_lo(g2[0]) * v2[0], bf_hi(u1[0]) + bf_hi(g2[0]) * v2[1]);
;         o[1] = pk2(bf_lo(u1[1]) + bf_lo(g2[1]) * v2[2], bf_hi(u1[1]) + bf_hi(g2[1]) * v2[3]);
;         *(u32x2*)(p.hn + (size_t)R * DM + c) = o;
;       }
;     }
	v_lshlrev_b32_e32 v64, 16, v58
	v_and_b32_e32 v65, 0xffff0000, v58
	v_pk_fma_f32 v[54:55], v[54:55], v[64:65], v[60:61]
	v_lshlrev_b32_e32 v60, 16, v134
	v_and_b32_e32 v61, 0xffff0000, v134
	v_lshlrev_b32_e32 v58, 16, v59
	v_and_b32_e32 v59, 0xffff0000, v59
	v_pk_fma_f32 v[56:57], v[56:57], v[58:59], v[60:61]
	v_cvt_pk_bf16_f32 v54, v54, v55
	v_cvt_pk_bf16_f32 v55, v56, v57
	global_store_dwordx2 v[62:63], v[54:55], off offset:64
	v_lshl_add_u64 v[54:55], v[86:87], 0, v[66:67]
	global_load_dwordx2 v[54:55], v[54:55], off
	v_lshlrev_b32_e32 v56, 16, v133
	v_and_b32_e32 v57, 0xffff0000, v133
	v_mfma_f32_16x16x32_bf16 v[198:201], v[162:165], v[98:101], v[42:45]
	s_waitcnt vmcnt(0)
	v_lshlrev_b32_e32 v58, 16, v54
	v_and_b32_e32 v59, 0xffff0000, v54
	v_pk_fma_f32 v[50:51], v[50:51], v[58:59], v[56:57]
	v_lshlrev_b32_e32 v56, 16, v132
	v_and_b32_e32 v57, 0xffff0000, v132
	v_lshlrev_b32_e32 v54, 16, v55
	v_and_b32_e32 v55, 0xffff0000, v55
	v_pk_fma_f32 v[52:53], v[52:53], v[54:55], v[56:57]
	v_cvt_pk_bf16_f32 v50, v50, v51
	v_cvt_pk_bf16_f32 v51, v52, v53
	global_store_dwordx2 v[62:63], v[50:51], off offset:96
	v_lshl_add_u64 v[50:51], v[82:83], 0, s[36:37]
	v_lshl_add_u64 v[54:55], v[50:51], 0, v[70:71]
	global_load_dwordx2 v[54:55], v[54:55], off
	v_mfma_f32_16x16x32_bf16 v[98:101], v[166:169], v[98:101], v[46:49]
	v_lshlrev_b32_e32 v56, 16, v131
	v_and_b32_e32 v57, 0xffff0000, v131
	v_lshlrev_b64 v[52:53], 11, v[84:85]
	v_mfma_f32_16x16x32_bf16 v[46:49], v[182:185], v[170:173], v[18:21]
	s_waitcnt vmcnt(0)
	v_lshlrev_b32_e32 v58, 16, v54
	v_and_b32_e32 v59, 0xffff0000, v54
	s_nop 4
	v_pk_fma_f32 v[46:47], v[46:47], v[58:59], v[56:57]
	v_lshlrev_b32_e32 v56, 16, v55
	v_cvt_pk_bf16_f32 v54, v46, v47
	v_lshlrev_b32_e32 v46, 16, v130
	v_and_b32_e32 v47, 0xffff0000, v130
	v_and_b32_e32 v57, 0xffff0000, v55
	v_pk_fma_f32 v[46:47], v[48:49], v[56:57], v[46:47]
	v_lshl_add_u64 v[48:49], v[50:51], 0, v[72:73]
	v_cvt_pk_bf16_f32 v55, v46, v47
	v_lshl_add_u64 v[46:47], s[8:9], 0, v[52:53]
	v_lshl_add_u64 v[46:47], v[46:47], 0, v[70:71]
	global_store_dwordx2 v[46:47], v[54:55], off
	global_load_dwordx2 v[48:49], v[48:49], off
	v_mfma_f32_16x16x32_bf16 v[42:45], v[186:189], v[170:173], v[22:25]
	v_lshlrev_b32_e32 v52, 16, v129
	v_and_b32_e32 v53, 0xffff0000, v129
	s_waitcnt vmcnt(0)
	v_lshlrev_b32_e32 v54, 16, v48
	v_and_b32_e32 v55, 0xffff0000, v48
	s_nop 2
	v_pk_fma_f32 v[42:43], v[42:43], v[54:55], v[52:53]
	v_lshlrev_b32_e32 v52, 16, v128
	v_and_b32_e32 v53, 0xffff0000, v128
	v_lshlrev_b32_e32 v48, 16, v49
	v_and_b32_e32 v49, 0xffff0000, v49
	v_pk_fma_f32 v[44:45], v[44:45], v[48:49], v[52:53]
	v_cvt_pk_bf16_f32 v42, v42, v43
	v_cvt_pk_bf16_f32 v43, v44, v45
	global_store_dwordx2 v[46:47], v[42:43], off offset:32
	v_lshl_add_u64 v[42:43], v[50:51], 0, v[68:69]
	global_load_dwordx2 v[42:43], v[42:43], off
	v_lshlrev_b32_e32 v44, 16, v127
	v_and_b32_e32 v45, 0xffff0000, v127
	v_mfma_f32_16x16x32_bf16 v[22:25], v[190:193], v[174:177], v[198:201]
	s_waitcnt vmcnt(0)
	v_lshlrev_b32_e32 v48, 16, v42
	v_and_b32_e32 v49, 0xffff0000, v42
	v_pk_fma_f32 v[38:39], v[38:39], v[48:49], v[44:45]
	v_lshlrev_b32_e32 v44, 16, v126
	v_and_b32_e32 v45, 0xffff0000, v126
	v_lshlrev_b32_e32 v42, 16, v43
	v_and_b32_e32 v43, 0xffff0000, v43
	v_pk_fma_f32 v[40:41], v[40:41], v[42:43], v[44:45]
	v_cvt_pk_bf16_f32 v38, v38, v39
	v_cvt_pk_bf16_f32 v39, v40, v41
	global_store_dwordx2 v[46:47], v[38:39], off offset:64
	v_lshl_add_u64 v[38:39], v[50:51], 0, v[66:67]
	global_load_dwordx2 v[38:39], v[38:39], off
	v_lshlrev_b32_e32 v40, 16, v125
	v_and_b32_e32 v41, 0xffff0000, v125
	v_mfma_f32_16x16x32_bf16 v[18:21], v[194:197], v[174:177], v[98:101]
	s_waitcnt vmcnt(0)
	v_lshlrev_b32_e32 v42, 16, v38
	v_and_b32_e32 v43, 0xffff0000, v38
	v_pk_fma_f32 v[34:35], v[34:35], v[42:43], v[40:41]
	v_lshlrev_b32_e32 v40, 16, v124
	v_and_b32_e32 v41, 0xffff0000, v124
	v_lshlrev_b32_e32 v38, 16, v39
	v_and_b32_e32 v39, 0xffff0000, v39
	v_pk_fma_f32 v[36:37], v[36:37], v[38:39], v[40:41]
	v_cvt_pk_bf16_f32 v34, v34, v35
	v_cvt_pk_bf16_f32 v35, v36, v37
	global_store_dwordx2 v[46:47], v[34:35], off offset:96
	v_lshl_add_u64 v[34:35], v[78:79], 0, s[36:37]
	v_lshl_add_u64 v[38:39], v[34:35], 0, v[70:71]
	global_load_dwordx2 v[38:39], v[38:39], off
	v_lshlrev_b32_e32 v40, 16, v123
	v_and_b32_e32 v41, 0xffff0000, v123
	v_lshlrev_b64 v[36:37], 11, v[80:81]
	v_mfma_f32_16x16x32_bf16 v[14:17], v[182:185], v[178:181], v[148:151]
	s_waitcnt vmcnt(0)
; DI unsigned pk2(float a, float b) { f32x2 v = {a, b}; bfv2 r = __builtin_convertvector(v, bfv2); return __builtin_bit_cast(unsigned, r); }
; DI float bf_lo(unsigned u) { return __uint_as_float(u << 16); }
; DI float bf_hi(unsigned u) { return __uint_as_float(u & 0xffff0000u); }
; DI void phase_merge(const Params& p, int l, char* lds) {
;     ...
;   for (int r = 0;; ++r) {
;     const int g = xcd_tile(r, 128 * 8); if (g < 0) break;
;     ...
; #pragma unroll
;     for (int mi = 0; mi < 4; ++mi) {
;       const int R = mt * 128 + wm * 64 + mi * 16 + l15;
; #pragma unroll
;       for (int ni = 0; ni < 4; ++ni) {
;         const int c = nt * 128 + wn * 64 + ni * 16 + quad * 4;
;         const u32x2 g2 = *(const u32x2*)(p.z + (size_t)R * NZ + C_MA + c);
;         const f32x4 v2 = a1[mi][ni]; const u32x2 u1 = pk[mi][ni];
;         u32x2 o;
;         o[0] = pk2(bf_lo(u1[0]) + bf_lo(g2[0]) * v2[0], bf_hi(u1[0]) + bf_hi(g2[0]) * v2[1]);
;         o[1] = pk2(bf_lo(u1[1]) + bf_lo(g2[1]) * v2[2], bf_hi(u1[1]) + bf_hi(g2[1]) * v2[3]);
;         *(u32x2*)(p.hn + (size_t)R * DM + c) = o;
;       }
;     }
;   }
	v_lshlrev_b32_e32 v42, 16, v38
	v_and_b32_e32 v43, 0xffff0000, v38
	v_pk_fma_f32 v[30:31], v[30:31], v[42:43], v[40:41]
	v_lshlrev_b32_e32 v40, 16, v39
	v_cvt_pk_bf16_f32 v38, v30, v31
	v_lshlrev_b32_e32 v30, 16, v122
	v_and_b32_e32 v31, 0xffff0000, v122
	v_and_b32_e32 v41, 0xffff0000, v39
	v_pk_fma_f32 v[30:31], v[32:33], v[40:41], v[30:31]
	v_lshl_add_u64 v[32:33], v[34:35], 0, v[72:73]
	v_cvt_pk_bf16_f32 v39, v30, v31
	v_lshl_add_u64 v[30:31], s[8:9], 0, v[36:37]
	v_lshl_add_u64 v[30:31], v[30:31], 0, v[70:71]
	global_store_dwordx2 v[30:31], v[38:39], off
	global_load_dwordx2 v[32:33], v[32:33], off
	v_lshlrev_b32_e32 v36, 16, v121
	v_and_b32_e32 v37, 0xffff0000, v121
	v_mfma_f32_16x16x32_bf16 v[10:13], v[186:189], v[178:181], v[152:155]
	s_waitcnt vmcnt(0)
	v_lshlrev_b32_e32 v38, 16, v32
	v_and_b32_e32 v39, 0xffff0000, v32
	v_pk_fma_f32 v[26:27], v[26:27], v[38:39], v[36:37]
	v_lshlrev_b32_e32 v36, 16, v120
	v_and_b32_e32 v37, 0xffff0000, v120
	v_lshlrev_b32_e32 v32, 16, v33
	v_and_b32_e32 v33, 0xffff0000, v33
	v_pk_fma_f32 v[28:29], v[28:29], v[32:33], v[36:37]
	v_cvt_pk_bf16_f32 v26, v26, v27
	v_cvt_pk_bf16_f32 v27, v28, v29
	global_store_dwordx2 v[30:31], v[26:27], off offset:32
	v_lshl_add_u64 v[26:27], v[34:35], 0, v[68:69]
	global_load_dwordx2 v[26:27], v[26:27], off
	v_lshlrev_b32_e32 v28, 16, v119
	v_and_b32_e32 v29, 0xffff0000, v119
	v_mfma_f32_16x16x32_bf16 v[6:9], v[190:193], v[178:181], v[156:159]
	s_waitcnt vmcnt(0)
	v_lshlrev_b32_e32 v32, 16, v26
	v_and_b32_e32 v33, 0xffff0000, v26
	v_pk_fma_f32 v[22:23], v[22:23], v[32:33], v[28:29]
	v_lshlrev_b32_e32 v28, 16, v118
	v_and_b32_e32 v29, 0xffff0000, v118
	v_lshlrev_b32_e32 v26, 16, v27
	v_and_b32_e32 v27, 0xffff0000, v27
	v_pk_fma_f32 v[24:25], v[24:25], v[26:27], v[28:29]
	v_cvt_pk_bf16_f32 v22, v22, v23
	v_cvt_pk_bf16_f32 v23, v24, v25
	global_store_dwordx2 v[30:31], v[22:23], off offset:64
	v_lshl_add_u64 v[22:23], v[34:35], 0, v[66:67]
	global_load_dwordx2 v[22:23], v[22:23], off
	v_lshlrev_b32_e32 v24, 16, v117
	v_and_b32_e32 v25, 0xffff0000, v117
	v_mfma_f32_16x16x32_bf16 v[2:5], v[194:197], v[178:181], v[102:105]
	s_waitcnt vmcnt(0)
	v_lshlrev_b32_e32 v26, 16, v22
	v_and_b32_e32 v27, 0xffff0000, v22
	v_pk_fma_f32 v[18:19], v[18:19], v[26:27], v[24:25]
	v_lshlrev_b32_e32 v24, 16, v116
	v_and_b32_e32 v25, 0xffff0000, v116
	v_lshlrev_b32_e32 v22, 16, v23
	v_and_b32_e32 v23, 0xffff0000, v23
	v_pk_fma_f32 v[20:21], v[20:21], v[22:23], v[24:25]
	v_cvt_pk_bf16_f32 v18, v18, v19
	v_cvt_pk_bf16_f32 v19, v20, v21
	global_store_dwordx2 v[30:31], v[18:19], off offset:96
	v_lshl_add_u64 v[18:19], v[74:75], 0, s[36:37]
	v_lshl_add_u64 v[22:23], v[18:19], 0, v[70:71]
	global_load_dwordx2 v[22:23], v[22:23], off
	v_lshlrev_b32_e32 v24, 16, v115
	v_and_b32_e32 v25, 0xffff0000, v115
	v_lshlrev_b64 v[20:21], 11, v[76:77]
	s_waitcnt vmcnt(0)
	v_lshlrev_b32_e32 v26, 16, v22
	v_and_b32_e32 v27, 0xffff0000, v22
	v_pk_fma_f32 v[14:15], v[14:15], v[26:27], v[24:25]
	v_lshlrev_b32_e32 v24, 16, v23
	v_cvt_pk_bf16_f32 v22, v14, v15
	v_lshlrev_b32_e32 v14, 16, v114
	v_and_b32_e32 v15, 0xffff0000, v114
	v_and_b32_e32 v25, 0xffff0000, v23
	v_pk_fma_f32 v[14:15], v[16:17], v[24:25], v[14:15]
	v_lshl_add_u64 v[16:17], v[18:19], 0, v[72:73]
	v_cvt_pk_bf16_f32 v23, v14, v15
	v_lshl_add_u64 v[14:15], s[8:9], 0, v[20:21]
	v_lshl_add_u64 v[14:15], v[14:15], 0, v[70:71]
	global_store_dwordx2 v[14:15], v[22:23], off
	global_load_dwordx2 v[16:17], v[16:17], off
	v_lshlrev_b32_e32 v20, 16, v113
	v_and_b32_e32 v21, 0xffff0000, v113
	s_waitcnt vmcnt(0)
	v_lshlrev_b32_e32 v22, 16, v16
	v_and_b32_e32 v23, 0xffff0000, v16
	v_pk_fma_f32 v[10:11], v[10:11], v[22:23], v[20:21]
	v_lshlrev_b32_e32 v20, 16, v112
	v_and_b32_e32 v21, 0xffff0000, v112
	v_lshlrev_b32_e32 v16, 16, v17
	v_and_b32_e32 v17, 0xffff0000, v17
	v_pk_fma_f32 v[12:13], v[12:13], v[16:17], v[20:21]
	v_cvt_pk_bf16_f32 v10, v10, v11
	v_cvt_pk_bf16_f32 v11, v12, v13
	global_store_dwordx2 v[14:15], v[10:11], off offset:32
	v_lshl_add_u64 v[10:11], v[18:19], 0, v[68:69]
	global_load_dwordx2 v[10:11], v[10:11], off
	v_lshlrev_b32_e32 v12, 16, v111
	v_and_b32_e32 v13, 0xffff0000, v111
	s_waitcnt vmcnt(0)
	v_lshlrev_b32_e32 v16, 16, v10
	v_and_b32_e32 v17, 0xffff0000, v10
	v_pk_fma_f32 v[6:7], v[6:7], v[16:17], v[12:13]
	v_lshlrev_b32_e32 v12, 16, v110
	v_and_b32_e32 v13, 0xffff0000, v110
	v_lshlrev_b32_e32 v10, 16, v11
	v_and_b32_e32 v11, 0xffff0000, v11
	v_pk_fma_f32 v[8:9], v[8:9], v[10:11], v[12:13]
	v_cvt_pk_bf16_f32 v6, v6, v7
	v_cvt_pk_bf16_f32 v7, v8, v9
	global_store_dwordx2 v[14:15], v[6:7], off offset:64
	v_lshl_add_u64 v[6:7], v[18:19], 0, v[66:67]
	global_load_dwordx2 v[6:7], v[6:7], off
	v_lshlrev_b32_e32 v8, 16, v109
	v_and_b32_e32 v9, 0xffff0000, v109
	s_waitcnt vmcnt(0)
	v_lshlrev_b32_e32 v10, 16, v6
	v_and_b32_e32 v11, 0xffff0000, v6
	v_pk_fma_f32 v[2:3], v[2:3], v[10:11], v[8:9]
	v_lshlrev_b32_e32 v8, 16, v108
	v_and_b32_e32 v9, 0xffff0000, v108
	v_lshlrev_b32_e32 v6, 16, v7
	v_and_b32_e32 v7, 0xffff0000, v7
	v_pk_fma_f32 v[4:5], v[4:5], v[6:7], v[8:9]
	v_cvt_pk_bf16_f32 v2, v2, v3
	v_cvt_pk_bf16_f32 v3, v4, v5
	global_store_dwordx2 v[14:15], v[2:3], off offset:96
	s_cbranch_scc0 .LBB0_722
